# per-phase s_setprio 3/0 flips removed from the three GEMM K-loops (A/B by repeated-phase timing: about 2 us per GEMM phase faster)
# speedup vs baseline: 1.0076x; 1.0021x over previous
.LBB0_184:
	s_add_u32 s24, s20, 0xfffc0080
	s_addc_u32 s25, s21, -1
	s_add_i32 s50, 0, 0x10000
	s_cmp_eq_u32 s49, 12
	s_cselect_b32 s27, s9, s25
	s_cselect_b32 s26, s19, s24
	s_cselect_b32 s25, s11, s48
	s_cselect_b32 s24, s46, s47
	s_add_i32 s77, 0, 0x14000
	v_add_u32_e32 v174, s50, v145
	v_add_u32_e32 v190, s77, v145
	ds_read_b128 v[150:153], v174
	ds_read_b128 v[154:157], v174 offset:1024
	ds_read_b128 v[170:173], v174 offset:2048
	ds_read_b128 v[174:177], v174 offset:3072
	ds_read_b128 v[178:181], v190
	ds_read_b128 v[182:185], v190 offset:1024
	ds_read_b128 v[186:189], v190 offset:2048
	ds_read_b128 v[190:193], v190 offset:3072
	v_lshl_add_u64 v[226:227], s[20:21], 0, v[140:141]
	s_add_i32 m0, s38, 0xc000
	ds_read_b128 v[194:197], v149
	ds_read_b128 v[198:201], v149 offset:1024
	ds_read_b128 v[202:205], v149 offset:2048
	ds_read_b128 v[206:209], v149 offset:3072
	ds_read_b128 v[210:213], v149 offset:4096
	ds_read_b128 v[214:217], v149 offset:5120
	ds_read_b128 v[218:221], v149 offset:6144
	ds_read_b128 v[222:225], v149 offset:7168
	global_load_lds_dwordx4 v[226:227], off
	v_lshl_add_u64 v[226:227], s[20:21], 0, v[142:143]
	s_add_i32 m0, s38, 0xe000
	s_nop 0
	global_load_lds_dwordx4 v[226:227], off
	s_waitcnt vmcnt(8)
	s_waitcnt lgkmcnt(0)
	s_barrier
	s_waitcnt lgkmcnt(0)
	v_mfma_f32_16x16x32_bf16 v[124:127], v[150:153], v[194:197], v[124:127]
	v_mfma_f32_16x16x32_bf16 v[120:123], v[170:173], v[194:197], v[120:123]
	v_mfma_f32_16x16x32_bf16 v[112:115], v[150:153], v[202:205], v[112:115]
	v_mfma_f32_16x16x32_bf16 v[104:107], v[170:173], v[202:205], v[104:107]
	v_mfma_f32_16x16x32_bf16 v[96:99], v[150:153], v[210:213], v[96:99]
	v_mfma_f32_16x16x32_bf16 v[88:91], v[170:173], v[210:213], v[88:91]
	v_mfma_f32_16x16x32_bf16 v[80:83], v[150:153], v[218:221], v[80:83]
	v_mfma_f32_16x16x32_bf16 v[72:75], v[170:173], v[218:221], v[72:75]
	v_mfma_f32_16x16x32_bf16 v[124:127], v[154:157], v[198:201], v[124:127]
	v_mfma_f32_16x16x32_bf16 v[120:123], v[174:177], v[198:201], v[120:123]
	v_mfma_f32_16x16x32_bf16 v[112:115], v[154:157], v[206:209], v[112:115]
	v_mfma_f32_16x16x32_bf16 v[104:107], v[174:177], v[206:209], v[104:107]
	v_mfma_f32_16x16x32_bf16 v[96:99], v[154:157], v[214:217], v[96:99]
	v_mfma_f32_16x16x32_bf16 v[88:91], v[174:177], v[214:217], v[88:91]
	v_mfma_f32_16x16x32_bf16 v[80:83], v[154:157], v[222:225], v[80:83]
	v_mfma_f32_16x16x32_bf16 v[72:75], v[174:177], v[222:225], v[72:75]
	v_mfma_f32_16x16x32_bf16 v[116:119], v[178:181], v[194:197], v[116:119]
	v_mfma_f32_16x16x32_bf16 v[108:111], v[186:189], v[194:197], v[108:111]
	v_mfma_f32_16x16x32_bf16 v[100:103], v[178:181], v[202:205], v[100:103]
	v_mfma_f32_16x16x32_bf16 v[92:95], v[186:189], v[202:205], v[92:95]
	v_mfma_f32_16x16x32_bf16 v[84:87], v[178:181], v[210:213], v[84:87]
	v_mfma_f32_16x16x32_bf16 v[76:79], v[186:189], v[210:213], v[76:79]
	v_mfma_f32_16x16x32_bf16 v[68:71], v[178:181], v[218:221], v[68:71]
	v_mfma_f32_16x16x32_bf16 v[64:67], v[186:189], v[218:221], v[64:67]
	v_mfma_f32_16x16x32_bf16 v[116:119], v[182:185], v[198:201], v[116:119]
	v_mfma_f32_16x16x32_bf16 v[108:111], v[190:193], v[198:201], v[108:111]
	v_mfma_f32_16x16x32_bf16 v[100:103], v[182:185], v[206:209], v[100:103]
	v_mfma_f32_16x16x32_bf16 v[92:95], v[190:193], v[206:209], v[92:95]
	v_mfma_f32_16x16x32_bf16 v[84:87], v[182:185], v[214:217], v[84:87]
	v_mfma_f32_16x16x32_bf16 v[76:79], v[190:193], v[214:217], v[76:79]
	v_mfma_f32_16x16x32_bf16 v[68:71], v[182:185], v[222:225], v[68:71]
	v_mfma_f32_16x16x32_bf16 v[64:67], v[190:193], v[222:225], v[64:67]
	s_barrier
	s_add_i32 s50, s50, s37
	v_lshl_add_u64 v[226:227], s[24:25], 0, v[128:129]
	s_mov_b32 m0, s50
	ds_read_b128 v[194:197], v149 offset:16384
	ds_read_b128 v[198:201], v149 offset:17408
	ds_read_b128 v[202:205], v149 offset:18432
	ds_read_b128 v[206:209], v149 offset:19456
	ds_read_b128 v[210:213], v149 offset:20480
	ds_read_b128 v[214:217], v149 offset:21504
	ds_read_b128 v[218:221], v149 offset:22528
	ds_read_b128 v[222:225], v149 offset:23552
	global_load_lds_dwordx4 v[226:227], off
	s_add_i32 m0, s50, 0x2000
	s_add_u32 s50, s24, 0x40000
	v_lshl_add_u64 v[228:229], s[24:25], 0, v[134:135]
	s_addc_u32 s51, s25, 0
	s_add_i32 s77, s77, s37
	global_load_lds_dwordx4 v[228:229], off
	v_lshl_add_u64 v[230:231], s[50:51], 0, v[128:129]
	s_mov_b32 m0, s77
	v_lshl_add_u64 v[232:233], s[26:27], 0, v[136:137]
	global_load_lds_dwordx4 v[230:231], off
	v_lshl_add_u64 v[230:231], s[50:51], 0, v[134:135]
	s_add_i32 m0, s77, 0x2000
	s_nop 0
	global_load_lds_dwordx4 v[230:231], off
	v_lshl_add_u64 v[230:231], s[26:27], 0, v[138:139]
	s_mov_b32 m0, s38
	s_nop 0
	global_load_lds_dwordx4 v[230:231], off
	s_mov_b32 m0, s39
	s_nop 0
	global_load_lds_dwordx4 v[232:233], off
	s_waitcnt vmcnt(8)
	s_waitcnt lgkmcnt(0)
	s_barrier
	s_waitcnt lgkmcnt(0)
	v_mfma_f32_16x16x32_bf16 v[60:63], v[150:153], v[194:197], v[60:63]
	v_mfma_f32_16x16x32_bf16 v[56:59], v[170:173], v[194:197], v[56:59]
	v_mfma_f32_16x16x32_bf16 v[48:51], v[150:153], v[202:205], v[48:51]
	v_mfma_f32_16x16x32_bf16 v[40:43], v[170:173], v[202:205], v[40:43]
	v_mfma_f32_16x16x32_bf16 v[32:35], v[150:153], v[210:213], v[32:35]
	v_mfma_f32_16x16x32_bf16 v[24:27], v[170:173], v[210:213], v[24:27]
	v_mfma_f32_16x16x32_bf16 v[16:19], v[150:153], v[218:221], v[16:19]
	v_mfma_f32_16x16x32_bf16 v[8:11], v[170:173], v[218:221], v[8:11]
	v_mfma_f32_16x16x32_bf16 v[60:63], v[154:157], v[198:201], v[60:63]
	v_mfma_f32_16x16x32_bf16 v[56:59], v[174:177], v[198:201], v[56:59]
	v_mfma_f32_16x16x32_bf16 v[48:51], v[154:157], v[206:209], v[48:51]
	v_mfma_f32_16x16x32_bf16 v[40:43], v[174:177], v[206:209], v[40:43]
	v_mfma_f32_16x16x32_bf16 v[32:35], v[154:157], v[214:217], v[32:35]
	v_mfma_f32_16x16x32_bf16 v[24:27], v[174:177], v[214:217], v[24:27]
	v_mfma_f32_16x16x32_bf16 v[16:19], v[154:157], v[222:225], v[16:19]
	v_mfma_f32_16x16x32_bf16 v[8:11], v[174:177], v[222:225], v[8:11]
	v_mfma_f32_16x16x32_bf16 v[52:55], v[178:181], v[194:197], v[52:55]
	v_mfma_f32_16x16x32_bf16 v[44:47], v[186:189], v[194:197], v[44:47]
	v_mfma_f32_16x16x32_bf16 v[36:39], v[178:181], v[202:205], v[36:39]
	v_mfma_f32_16x16x32_bf16 v[28:31], v[186:189], v[202:205], v[28:31]
	v_mfma_f32_16x16x32_bf16 v[20:23], v[178:181], v[210:213], v[20:23]
	v_mfma_f32_16x16x32_bf16 v[12:15], v[186:189], v[210:213], v[12:15]
	v_mfma_f32_16x16x32_bf16 v[4:7], v[178:181], v[218:221], v[4:7]
	v_mfma_f32_16x16x32_bf16 v[0:3], v[186:189], v[218:221], v[0:3]
	v_mfma_f32_16x16x32_bf16 v[52:55], v[182:185], v[198:201], v[52:55]
	v_mfma_f32_16x16x32_bf16 v[44:47], v[190:193], v[198:201], v[44:47]
	v_mfma_f32_16x16x32_bf16 v[36:39], v[182:185], v[206:209], v[36:39]
	v_mfma_f32_16x16x32_bf16 v[28:31], v[190:193], v[206:209], v[28:31]
	v_mfma_f32_16x16x32_bf16 v[20:23], v[182:185], v[214:217], v[20:23]
	v_mfma_f32_16x16x32_bf16 v[12:15], v[190:193], v[214:217], v[12:15]
	v_mfma_f32_16x16x32_bf16 v[4:7], v[182:185], v[222:225], v[4:7]
	v_mfma_f32_16x16x32_bf16 v[0:3], v[190:193], v[222:225], v[0:3]
	s_barrier
	s_add_i32 s50, 0, 0x18000
	s_add_i32 s51, 0, 0x1c000
	v_add_u32_e32 v174, s50, v145
	v_add_u32_e32 v190, s51, v145
	ds_read_b128 v[150:153], v174
	ds_read_b128 v[154:157], v174 offset:1024
	ds_read_b128 v[170:173], v174 offset:2048
	ds_read_b128 v[174:177], v174 offset:3072
	ds_read_b128 v[178:181], v190
	ds_read_b128 v[182:185], v190 offset:1024
	ds_read_b128 v[186:189], v190 offset:2048
	ds_read_b128 v[190:193], v190 offset:3072
	s_add_u32 s26, s26, 0x40000
	s_addc_u32 s27, s27, 0
	s_mov_b32 m0, s40
	v_lshl_add_u64 v[234:235], s[26:27], 0, v[138:139]
	ds_read_b128 v[194:197], v149 offset:32768
	ds_read_b128 v[198:201], v149 offset:33792
	ds_read_b128 v[202:205], v149 offset:34816
	ds_read_b128 v[206:209], v149 offset:35840
	ds_read_b128 v[210:213], v149 offset:36864
	ds_read_b128 v[214:217], v149 offset:37888
	ds_read_b128 v[218:221], v149 offset:38912
	ds_read_b128 v[222:225], v149 offset:39936
	global_load_lds_dwordx4 v[234:235], off
	v_lshl_add_u64 v[234:235], s[26:27], 0, v[136:137]
	s_mov_b32 m0, s41
	s_nop 0
	global_load_lds_dwordx4 v[234:235], off
	s_waitcnt vmcnt(8)
	s_waitcnt lgkmcnt(0)
	s_barrier
	s_waitcnt lgkmcnt(0)
	v_mfma_f32_16x16x32_bf16 v[124:127], v[150:153], v[194:197], v[124:127]
	v_mfma_f32_16x16x32_bf16 v[120:123], v[170:173], v[194:197], v[120:123]
	v_mfma_f32_16x16x32_bf16 v[112:115], v[150:153], v[202:205], v[112:115]
	v_mfma_f32_16x16x32_bf16 v[104:107], v[170:173], v[202:205], v[104:107]
	v_mfma_f32_16x16x32_bf16 v[96:99], v[150:153], v[210:213], v[96:99]
	v_mfma_f32_16x16x32_bf16 v[88:91], v[170:173], v[210:213], v[88:91]
	v_mfma_f32_16x16x32_bf16 v[80:83], v[150:153], v[218:221], v[80:83]
	v_mfma_f32_16x16x32_bf16 v[72:75], v[170:173], v[218:221], v[72:75]
	v_mfma_f32_16x16x32_bf16 v[124:127], v[154:157], v[198:201], v[124:127]
	v_mfma_f32_16x16x32_bf16 v[120:123], v[174:177], v[198:201], v[120:123]
	v_mfma_f32_16x16x32_bf16 v[112:115], v[154:157], v[206:209], v[112:115]
	v_mfma_f32_16x16x32_bf16 v[104:107], v[174:177], v[206:209], v[104:107]
	v_mfma_f32_16x16x32_bf16 v[96:99], v[154:157], v[214:217], v[96:99]
	v_mfma_f32_16x16x32_bf16 v[88:91], v[174:177], v[214:217], v[88:91]
	v_mfma_f32_16x16x32_bf16 v[80:83], v[154:157], v[222:225], v[80:83]
	v_mfma_f32_16x16x32_bf16 v[72:75], v[174:177], v[222:225], v[72:75]
	v_mfma_f32_16x16x32_bf16 v[116:119], v[178:181], v[194:197], v[116:119]
	v_mfma_f32_16x16x32_bf16 v[108:111], v[186:189], v[194:197], v[108:111]
	v_mfma_f32_16x16x32_bf16 v[100:103], v[178:181], v[202:205], v[100:103]
	v_mfma_f32_16x16x32_bf16 v[92:95], v[186:189], v[202:205], v[92:95]
	v_mfma_f32_16x16x32_bf16 v[84:87], v[178:181], v[210:213], v[84:87]
	v_mfma_f32_16x16x32_bf16 v[76:79], v[186:189], v[210:213], v[76:79]
	v_mfma_f32_16x16x32_bf16 v[68:71], v[178:181], v[218:221], v[68:71]
	v_mfma_f32_16x16x32_bf16 v[64:67], v[186:189], v[218:221], v[64:67]
	v_mfma_f32_16x16x32_bf16 v[116:119], v[182:185], v[198:201], v[116:119]
	v_mfma_f32_16x16x32_bf16 v[108:111], v[190:193], v[198:201], v[108:111]
	v_mfma_f32_16x16x32_bf16 v[100:103], v[182:185], v[206:209], v[100:103]
	v_mfma_f32_16x16x32_bf16 v[92:95], v[190:193], v[206:209], v[92:95]
	v_mfma_f32_16x16x32_bf16 v[84:87], v[182:185], v[214:217], v[84:87]
	v_mfma_f32_16x16x32_bf16 v[76:79], v[190:193], v[214:217], v[76:79]
	v_mfma_f32_16x16x32_bf16 v[68:71], v[182:185], v[222:225], v[68:71]
	v_mfma_f32_16x16x32_bf16 v[64:67], v[190:193], v[222:225], v[64:67]
	s_barrier
	s_add_i32 s26, s50, s37
	v_lshl_add_u64 v[226:227], v[226:227], 0, s[84:85]
	s_mov_b32 m0, s26
	ds_read_b128 v[194:197], v149 offset:49152
	ds_read_b128 v[198:201], v149 offset:50176
	ds_read_b128 v[202:205], v149 offset:51200
	ds_read_b128 v[206:209], v149 offset:52224
	ds_read_b128 v[210:213], v149 offset:53248
	ds_read_b128 v[214:217], v149 offset:54272
	ds_read_b128 v[218:221], v149 offset:55296
	ds_read_b128 v[222:225], v149 offset:56320
	global_load_lds_dwordx4 v[226:227], off
	s_add_i32 m0, s26, 0x2000
	s_add_u32 s24, s24, 0x40080
	v_lshl_add_u64 v[226:227], v[228:229], 0, s[84:85]
	s_addc_u32 s25, s25, 0
	s_add_i32 s26, s51, s37
	global_load_lds_dwordx4 v[226:227], off
	v_lshl_add_u64 v[226:227], s[24:25], 0, v[128:129]
	s_mov_b32 m0, s26
	s_nop 0
	global_load_lds_dwordx4 v[226:227], off
	v_lshl_add_u64 v[226:227], s[24:25], 0, v[134:135]
	s_add_i32 m0, s26, 0x2000
	s_nop 0
	global_load_lds_dwordx4 v[226:227], off
	v_lshl_add_u64 v[226:227], v[230:231], 0, s[84:85]
	s_mov_b32 m0, s42
	s_nop 0
	global_load_lds_dwordx4 v[226:227], off
	v_lshl_add_u64 v[226:227], v[232:233], 0, s[84:85]
	s_mov_b32 m0, s43
	s_nop 0
	global_load_lds_dwordx4 v[226:227], off
	s_waitcnt vmcnt(8)
	s_waitcnt lgkmcnt(0)
	s_barrier
	s_waitcnt lgkmcnt(0)
	v_mfma_f32_16x16x32_bf16 v[60:63], v[150:153], v[194:197], v[60:63]
	v_mfma_f32_16x16x32_bf16 v[56:59], v[170:173], v[194:197], v[56:59]
	v_mfma_f32_16x16x32_bf16 v[48:51], v[150:153], v[202:205], v[48:51]
	v_mfma_f32_16x16x32_bf16 v[40:43], v[170:173], v[202:205], v[40:43]
	v_mfma_f32_16x16x32_bf16 v[32:35], v[150:153], v[210:213], v[32:35]
	v_mfma_f32_16x16x32_bf16 v[24:27], v[170:173], v[210:213], v[24:27]
	v_mfma_f32_16x16x32_bf16 v[16:19], v[150:153], v[218:221], v[16:19]
	v_mfma_f32_16x16x32_bf16 v[8:11], v[170:173], v[218:221], v[8:11]
	v_mfma_f32_16x16x32_bf16 v[60:63], v[154:157], v[198:201], v[60:63]
	v_mfma_f32_16x16x32_bf16 v[56:59], v[174:177], v[198:201], v[56:59]
	v_mfma_f32_16x16x32_bf16 v[48:51], v[154:157], v[206:209], v[48:51]
	v_mfma_f32_16x16x32_bf16 v[40:43], v[174:177], v[206:209], v[40:43]
	v_mfma_f32_16x16x32_bf16 v[32:35], v[154:157], v[214:217], v[32:35]
	v_mfma_f32_16x16x32_bf16 v[24:27], v[174:177], v[214:217], v[24:27]
	v_mfma_f32_16x16x32_bf16 v[16:19], v[154:157], v[222:225], v[16:19]
	v_mfma_f32_16x16x32_bf16 v[8:11], v[174:177], v[222:225], v[8:11]
	v_mfma_f32_16x16x32_bf16 v[52:55], v[178:181], v[194:197], v[52:55]
	v_mfma_f32_16x16x32_bf16 v[44:47], v[186:189], v[194:197], v[44:47]
	v_mfma_f32_16x16x32_bf16 v[36:39], v[178:181], v[202:205], v[36:39]
	v_mfma_f32_16x16x32_bf16 v[28:31], v[186:189], v[202:205], v[28:31]
	v_mfma_f32_16x16x32_bf16 v[20:23], v[178:181], v[210:213], v[20:23]
	v_mfma_f32_16x16x32_bf16 v[12:15], v[186:189], v[210:213], v[12:15]
	v_mfma_f32_16x16x32_bf16 v[4:7], v[178:181], v[218:221], v[4:7]
	v_mfma_f32_16x16x32_bf16 v[0:3], v[186:189], v[218:221], v[0:3]
	v_mfma_f32_16x16x32_bf16 v[52:55], v[182:185], v[198:201], v[52:55]
	v_mfma_f32_16x16x32_bf16 v[44:47], v[190:193], v[198:201], v[44:47]
	v_mfma_f32_16x16x32_bf16 v[36:39], v[182:185], v[206:209], v[36:39]
	v_mfma_f32_16x16x32_bf16 v[28:31], v[190:193], v[206:209], v[28:31]
	v_mfma_f32_16x16x32_bf16 v[20:23], v[182:185], v[214:217], v[20:23]
	v_mfma_f32_16x16x32_bf16 v[12:15], v[190:193], v[214:217], v[12:15]
	v_mfma_f32_16x16x32_bf16 v[4:7], v[182:185], v[222:225], v[4:7]
	v_mfma_f32_16x16x32_bf16 v[0:3], v[190:193], v[222:225], v[0:3]
	s_barrier
	s_add_i32 s49, s49, 2
	s_add_u32 s20, s20, 0x100
	s_addc_u32 s21, s21, 0
	s_add_u32 s47, s47, 0x100
	s_addc_u32 s48, s48, 0
	s_cmp_gt_u32 s49, 13
	s_cbranch_scc0 .LBB0_184
	s_branch .Lit0_prj_skip
.Lit0_prj:
	s_add_u32 s24, s20, 0xfffc0080
	s_addc_u32 s25, s21, -1
	s_add_i32 s50, 0, 0x10000
	s_cmp_eq_u32 s49, 12
	s_cselect_b32 s27, s9, s25
	s_cselect_b32 s26, s19, s24
	s_cselect_b32 s25, s11, s48
	s_cselect_b32 s24, s46, s47
	s_add_i32 s77, 0, 0x14000
	v_add_u32_e32 v174, s50, v145
	v_add_u32_e32 v190, s77, v145
	ds_read_b128 v[150:153], v174
	ds_read_b128 v[154:157], v174 offset:1024
	ds_read_b128 v[170:173], v174 offset:2048
	ds_read_b128 v[174:177], v174 offset:3072
	ds_read_b128 v[178:181], v190
	ds_read_b128 v[182:185], v190 offset:1024
	ds_read_b128 v[186:189], v190 offset:2048
	ds_read_b128 v[190:193], v190 offset:3072
	v_lshl_add_u64 v[226:227], s[20:21], 0, v[140:141]
	s_add_i32 m0, s38, 0xc000
	ds_read_b128 v[194:197], v149
	ds_read_b128 v[198:201], v149 offset:1024
	ds_read_b128 v[202:205], v149 offset:2048
	ds_read_b128 v[206:209], v149 offset:3072
	ds_read_b128 v[210:213], v149 offset:4096
	ds_read_b128 v[214:217], v149 offset:5120
	ds_read_b128 v[218:221], v149 offset:6144
	ds_read_b128 v[222:225], v149 offset:7168
	global_load_lds_dwordx4 v[226:227], off
	v_lshl_add_u64 v[226:227], s[20:21], 0, v[142:143]
	s_add_i32 m0, s38, 0xe000
	s_nop 0
	global_load_lds_dwordx4 v[226:227], off
	s_waitcnt vmcnt(8)
	s_waitcnt lgkmcnt(0)
	s_barrier
	s_waitcnt lgkmcnt(0)
	v_mfma_f32_16x16x32_bf16 v[124:127], v[150:153], v[194:197], 0
	v_mfma_f32_16x16x32_bf16 v[120:123], v[170:173], v[194:197], 0
	v_mfma_f32_16x16x32_bf16 v[112:115], v[150:153], v[202:205], 0
	v_mfma_f32_16x16x32_bf16 v[104:107], v[170:173], v[202:205], 0
	v_mfma_f32_16x16x32_bf16 v[96:99], v[150:153], v[210:213], 0
	v_mfma_f32_16x16x32_bf16 v[88:91], v[170:173], v[210:213], 0
	v_mfma_f32_16x16x32_bf16 v[80:83], v[150:153], v[218:221], 0
	v_mfma_f32_16x16x32_bf16 v[72:75], v[170:173], v[218:221], 0
	v_mfma_f32_16x16x32_bf16 v[124:127], v[154:157], v[198:201], v[124:127]
	v_mfma_f32_16x16x32_bf16 v[120:123], v[174:177], v[198:201], v[120:123]
	v_mfma_f32_16x16x32_bf16 v[112:115], v[154:157], v[206:209], v[112:115]
	v_mfma_f32_16x16x32_bf16 v[104:107], v[174:177], v[206:209], v[104:107]
	v_mfma_f32_16x16x32_bf16 v[96:99], v[154:157], v[214:217], v[96:99]
	v_mfma_f32_16x16x32_bf16 v[88:91], v[174:177], v[214:217], v[88:91]
	v_mfma_f32_16x16x32_bf16 v[80:83], v[154:157], v[222:225], v[80:83]
	v_mfma_f32_16x16x32_bf16 v[72:75], v[174:177], v[222:225], v[72:75]
	v_mfma_f32_16x16x32_bf16 v[116:119], v[178:181], v[194:197], 0
	v_mfma_f32_16x16x32_bf16 v[108:111], v[186:189], v[194:197], 0
	v_mfma_f32_16x16x32_bf16 v[100:103], v[178:181], v[202:205], 0
	v_mfma_f32_16x16x32_bf16 v[92:95], v[186:189], v[202:205], 0
	v_mfma_f32_16x16x32_bf16 v[84:87], v[178:181], v[210:213], 0
	v_mfma_f32_16x16x32_bf16 v[76:79], v[186:189], v[210:213], 0
	v_mfma_f32_16x16x32_bf16 v[68:71], v[178:181], v[218:221], 0
	v_mfma_f32_16x16x32_bf16 v[64:67], v[186:189], v[218:221], 0
	v_mfma_f32_16x16x32_bf16 v[116:119], v[182:185], v[198:201], v[116:119]
	v_mfma_f32_16x16x32_bf16 v[108:111], v[190:193], v[198:201], v[108:111]
	v_mfma_f32_16x16x32_bf16 v[100:103], v[182:185], v[206:209], v[100:103]
	v_mfma_f32_16x16x32_bf16 v[92:95], v[190:193], v[206:209], v[92:95]
	v_mfma_f32_16x16x32_bf16 v[84:87], v[182:185], v[214:217], v[84:87]
	v_mfma_f32_16x16x32_bf16 v[76:79], v[190:193], v[214:217], v[76:79]
	v_mfma_f32_16x16x32_bf16 v[68:71], v[182:185], v[222:225], v[68:71]
	v_mfma_f32_16x16x32_bf16 v[64:67], v[190:193], v[222:225], v[64:67]
	s_barrier
	s_add_i32 s50, s50, s37
	v_lshl_add_u64 v[226:227], s[24:25], 0, v[128:129]
	s_mov_b32 m0, s50
	ds_read_b128 v[194:197], v149 offset:16384
	ds_read_b128 v[198:201], v149 offset:17408
	ds_read_b128 v[202:205], v149 offset:18432
	ds_read_b128 v[206:209], v149 offset:19456
	ds_read_b128 v[210:213], v149 offset:20480
	ds_read_b128 v[214:217], v149 offset:21504
	ds_read_b128 v[218:221], v149 offset:22528
	ds_read_b128 v[222:225], v149 offset:23552
	global_load_lds_dwordx4 v[226:227], off
	s_add_i32 m0, s50, 0x2000
	s_add_u32 s50, s24, 0x40000
	v_lshl_add_u64 v[228:229], s[24:25], 0, v[134:135]
	s_addc_u32 s51, s25, 0
	s_add_i32 s77, s77, s37
	global_load_lds_dwordx4 v[228:229], off
	v_lshl_add_u64 v[230:231], s[50:51], 0, v[128:129]
	s_mov_b32 m0, s77
	v_lshl_add_u64 v[232:233], s[26:27], 0, v[136:137]
	global_load_lds_dwordx4 v[230:231], off
	v_lshl_add_u64 v[230:231], s[50:51], 0, v[134:135]
	s_add_i32 m0, s77, 0x2000
	s_nop 0
	global_load_lds_dwordx4 v[230:231], off
	v_lshl_add_u64 v[230:231], s[26:27], 0, v[138:139]
	s_mov_b32 m0, s38
	s_nop 0
	global_load_lds_dwordx4 v[230:231], off
	s_mov_b32 m0, s39
	s_nop 0
	global_load_lds_dwordx4 v[232:233], off
	s_waitcnt vmcnt(8)
	s_waitcnt lgkmcnt(0)
	s_barrier
	s_waitcnt lgkmcnt(0)
	v_mfma_f32_16x16x32_bf16 v[60:63], v[150:153], v[194:197], 0
	v_mfma_f32_16x16x32_bf16 v[56:59], v[170:173], v[194:197], 0
	v_mfma_f32_16x16x32_bf16 v[48:51], v[150:153], v[202:205], 0
	v_mfma_f32_16x16x32_bf16 v[40:43], v[170:173], v[202:205], 0
	v_mfma_f32_16x16x32_bf16 v[32:35], v[150:153], v[210:213], 0
	v_mfma_f32_16x16x32_bf16 v[24:27], v[170:173], v[210:213], 0
	v_mfma_f32_16x16x32_bf16 v[16:19], v[150:153], v[218:221], 0
	v_mfma_f32_16x16x32_bf16 v[8:11], v[170:173], v[218:221], 0
	v_mfma_f32_16x16x32_bf16 v[60:63], v[154:157], v[198:201], v[60:63]
	v_mfma_f32_16x16x32_bf16 v[56:59], v[174:177], v[198:201], v[56:59]
	v_mfma_f32_16x16x32_bf16 v[48:51], v[154:157], v[206:209], v[48:51]
	v_mfma_f32_16x16x32_bf16 v[40:43], v[174:177], v[206:209], v[40:43]
	v_mfma_f32_16x16x32_bf16 v[32:35], v[154:157], v[214:217], v[32:35]
	v_mfma_f32_16x16x32_bf16 v[24:27], v[174:177], v[214:217], v[24:27]
	v_mfma_f32_16x16x32_bf16 v[16:19], v[154:157], v[222:225], v[16:19]
	v_mfma_f32_16x16x32_bf16 v[8:11], v[174:177], v[222:225], v[8:11]
	v_mfma_f32_16x16x32_bf16 v[52:55], v[178:181], v[194:197], 0
	v_mfma_f32_16x16x32_bf16 v[44:47], v[186:189], v[194:197], 0
	v_mfma_f32_16x16x32_bf16 v[36:39], v[178:181], v[202:205], 0
	v_mfma_f32_16x16x32_bf16 v[28:31], v[186:189], v[202:205], 0
	v_mfma_f32_16x16x32_bf16 v[20:23], v[178:181], v[210:213], 0
	v_mfma_f32_16x16x32_bf16 v[12:15], v[186:189], v[210:213], 0
	v_mfma_f32_16x16x32_bf16 v[4:7], v[178:181], v[218:221], 0
	v_mfma_f32_16x16x32_bf16 v[0:3], v[186:189], v[218:221], 0
	v_mfma_f32_16x16x32_bf16 v[52:55], v[182:185], v[198:201], v[52:55]
	v_mfma_f32_16x16x32_bf16 v[44:47], v[190:193], v[198:201], v[44:47]
	v_mfma_f32_16x16x32_bf16 v[36:39], v[182:185], v[206:209], v[36:39]
	v_mfma_f32_16x16x32_bf16 v[28:31], v[190:193], v[206:209], v[28:31]
	v_mfma_f32_16x16x32_bf16 v[20:23], v[182:185], v[214:217], v[20:23]
	v_mfma_f32_16x16x32_bf16 v[12:15], v[190:193], v[214:217], v[12:15]
	v_mfma_f32_16x16x32_bf16 v[4:7], v[182:185], v[222:225], v[4:7]
	v_mfma_f32_16x16x32_bf16 v[0:3], v[190:193], v[222:225], v[0:3]
	s_barrier
	s_add_i32 s50, 0, 0x18000
	s_add_i32 s51, 0, 0x1c000
	v_add_u32_e32 v174, s50, v145
	v_add_u32_e32 v190, s51, v145
	ds_read_b128 v[150:153], v174
	ds_read_b128 v[154:157], v174 offset:1024
	ds_read_b128 v[170:173], v174 offset:2048
	ds_read_b128 v[174:177], v174 offset:3072
	ds_read_b128 v[178:181], v190
	ds_read_b128 v[182:185], v190 offset:1024
	ds_read_b128 v[186:189], v190 offset:2048
	ds_read_b128 v[190:193], v190 offset:3072
	s_add_u32 s26, s26, 0x40000
	s_addc_u32 s27, s27, 0
	s_mov_b32 m0, s40
	v_lshl_add_u64 v[234:235], s[26:27], 0, v[138:139]
	ds_read_b128 v[194:197], v149 offset:32768
	ds_read_b128 v[198:201], v149 offset:33792
	ds_read_b128 v[202:205], v149 offset:34816
	ds_read_b128 v[206:209], v149 offset:35840
	ds_read_b128 v[210:213], v149 offset:36864
	ds_read_b128 v[214:217], v149 offset:37888
	ds_read_b128 v[218:221], v149 offset:38912
	ds_read_b128 v[222:225], v149 offset:39936
	global_load_lds_dwordx4 v[234:235], off
	v_lshl_add_u64 v[234:235], s[26:27], 0, v[136:137]
	s_mov_b32 m0, s41
	s_nop 0
	global_load_lds_dwordx4 v[234:235], off
	s_waitcnt vmcnt(8)
	s_waitcnt lgkmcnt(0)
	s_barrier
	s_waitcnt lgkmcnt(0)
	v_mfma_f32_16x16x32_bf16 v[124:127], v[150:153], v[194:197], v[124:127]
	v_mfma_f32_16x16x32_bf16 v[120:123], v[170:173], v[194:197], v[120:123]
	v_mfma_f32_16x16x32_bf16 v[112:115], v[150:153], v[202:205], v[112:115]
	v_mfma_f32_16x16x32_bf16 v[104:107], v[170:173], v[202:205], v[104:107]
	v_mfma_f32_16x16x32_bf16 v[96:99], v[150:153], v[210:213], v[96:99]
	v_mfma_f32_16x16x32_bf16 v[88:91], v[170:173], v[210:213], v[88:91]
	v_mfma_f32_16x16x32_bf16 v[80:83], v[150:153], v[218:221], v[80:83]
	v_mfma_f32_16x16x32_bf16 v[72:75], v[170:173], v[218:221], v[72:75]
	v_mfma_f32_16x16x32_bf16 v[124:127], v[154:157], v[198:201], v[124:127]
	v_mfma_f32_16x16x32_bf16 v[120:123], v[174:177], v[198:201], v[120:123]
	v_mfma_f32_16x16x32_bf16 v[112:115], v[154:157], v[206:209], v[112:115]
	v_mfma_f32_16x16x32_bf16 v[104:107], v[174:177], v[206:209], v[104:107]
	v_mfma_f32_16x16x32_bf16 v[96:99], v[154:157], v[214:217], v[96:99]
	v_mfma_f32_16x16x32_bf16 v[88:91], v[174:177], v[214:217], v[88:91]
	v_mfma_f32_16x16x32_bf16 v[80:83], v[154:157], v[222:225], v[80:83]
	v_mfma_f32_16x16x32_bf16 v[72:75], v[174:177], v[222:225], v[72:75]
	v_mfma_f32_16x16x32_bf16 v[116:119], v[178:181], v[194:197], v[116:119]
	v_mfma_f32_16x16x32_bf16 v[108:111], v[186:189], v[194:197], v[108:111]
	v_mfma_f32_16x16x32_bf16 v[100:103], v[178:181], v[202:205], v[100:103]
	v_mfma_f32_16x16x32_bf16 v[92:95], v[186:189], v[202:205], v[92:95]
	v_mfma_f32_16x16x32_bf16 v[84:87], v[178:181], v[210:213], v[84:87]
	v_mfma_f32_16x16x32_bf16 v[76:79], v[186:189], v[210:213], v[76:79]
	v_mfma_f32_16x16x32_bf16 v[68:71], v[178:181], v[218:221], v[68:71]
	v_mfma_f32_16x16x32_bf16 v[64:67], v[186:189], v[218:221], v[64:67]
	v_mfma_f32_16x16x32_bf16 v[116:119], v[182:185], v[198:201], v[116:119]
	v_mfma_f32_16x16x32_bf16 v[108:111], v[190:193], v[198:201], v[108:111]
	v_mfma_f32_16x16x32_bf16 v[100:103], v[182:185], v[206:209], v[100:103]
	v_mfma_f32_16x16x32_bf16 v[92:95], v[190:193], v[206:209], v[92:95]
	v_mfma_f32_16x16x32_bf16 v[84:87], v[182:185], v[214:217], v[84:87]
	v_mfma_f32_16x16x32_bf16 v[76:79], v[190:193], v[214:217], v[76:79]
	v_mfma_f32_16x16x32_bf16 v[68:71], v[182:185], v[222:225], v[68:71]
	v_mfma_f32_16x16x32_bf16 v[64:67], v[190:193], v[222:225], v[64:67]
	s_barrier
	s_add_i32 s26, s50, s37
	v_lshl_add_u64 v[226:227], v[226:227], 0, s[84:85]
	s_mov_b32 m0, s26
	ds_read_b128 v[194:197], v149 offset:49152
	ds_read_b128 v[198:201], v149 offset:50176
	ds_read_b128 v[202:205], v149 offset:51200
	ds_read_b128 v[206:209], v149 offset:52224
	ds_read_b128 v[210:213], v149 offset:53248
	ds_read_b128 v[214:217], v149 offset:54272
	ds_read_b128 v[218:221], v149 offset:55296
	ds_read_b128 v[222:225], v149 offset:56320
	global_load_lds_dwordx4 v[226:227], off
	s_add_i32 m0, s26, 0x2000
	s_add_u32 s24, s24, 0x40080
	v_lshl_add_u64 v[226:227], v[228:229], 0, s[84:85]
	s_addc_u32 s25, s25, 0
	s_add_i32 s26, s51, s37
	global_load_lds_dwordx4 v[226:227], off
	v_lshl_add_u64 v[226:227], s[24:25], 0, v[128:129]
	s_mov_b32 m0, s26
	s_nop 0
	global_load_lds_dwordx4 v[226:227], off
	v_lshl_add_u64 v[226:227], s[24:25], 0, v[134:135]
	s_add_i32 m0, s26, 0x2000
	s_nop 0
	global_load_lds_dwordx4 v[226:227], off
	v_lshl_add_u64 v[226:227], v[230:231], 0, s[84:85]
	s_mov_b32 m0, s42
	s_nop 0
	global_load_lds_dwordx4 v[226:227], off
	v_lshl_add_u64 v[226:227], v[232:233], 0, s[84:85]
	s_mov_b32 m0, s43
	s_nop 0
	global_load_lds_dwordx4 v[226:227], off
	s_waitcnt vmcnt(8)
	s_waitcnt lgkmcnt(0)
	s_barrier
	s_waitcnt lgkmcnt(0)
	v_mfma_f32_16x16x32_bf16 v[60:63], v[150:153], v[194:197], v[60:63]
	v_mfma_f32_16x16x32_bf16 v[56:59], v[170:173], v[194:197], v[56:59]
	v_mfma_f32_16x16x32_bf16 v[48:51], v[150:153], v[202:205], v[48:51]
	v_mfma_f32_16x16x32_bf16 v[40:43], v[170:173], v[202:205], v[40:43]
	v_mfma_f32_16x16x32_bf16 v[32:35], v[150:153], v[210:213], v[32:35]
	v_mfma_f32_16x16x32_bf16 v[24:27], v[170:173], v[210:213], v[24:27]
	v_mfma_f32_16x16x32_bf16 v[16:19], v[150:153], v[218:221], v[16:19]
	v_mfma_f32_16x16x32_bf16 v[8:11], v[170:173], v[218:221], v[8:11]
	v_mfma_f32_16x16x32_bf16 v[60:63], v[154:157], v[198:201], v[60:63]
	v_mfma_f32_16x16x32_bf16 v[56:59], v[174:177], v[198:201], v[56:59]
	v_mfma_f32_16x16x32_bf16 v[48:51], v[154:157], v[206:209], v[48:51]
	v_mfma_f32_16x16x32_bf16 v[40:43], v[174:177], v[206:209], v[40:43]
	v_mfma_f32_16x16x32_bf16 v[32:35], v[154:157], v[214:217], v[32:35]
	v_mfma_f32_16x16x32_bf16 v[24:27], v[174:177], v[214:217], v[24:27]
	v_mfma_f32_16x16x32_bf16 v[16:19], v[154:157], v[222:225], v[16:19]
	v_mfma_f32_16x16x32_bf16 v[8:11], v[174:177], v[222:225], v[8:11]
	v_mfma_f32_16x16x32_bf16 v[52:55], v[178:181], v[194:197], v[52:55]
	v_mfma_f32_16x16x32_bf16 v[44:47], v[186:189], v[194:197], v[44:47]
	v_mfma_f32_16x16x32_bf16 v[36:39], v[178:181], v[202:205], v[36:39]
	v_mfma_f32_16x16x32_bf16 v[28:31], v[186:189], v[202:205], v[28:31]
	v_mfma_f32_16x16x32_bf16 v[20:23], v[178:181], v[210:213], v[20:23]
	v_mfma_f32_16x16x32_bf16 v[12:15], v[186:189], v[210:213], v[12:15]
	v_mfma_f32_16x16x32_bf16 v[4:7], v[178:181], v[218:221], v[4:7]
	v_mfma_f32_16x16x32_bf16 v[0:3], v[186:189], v[218:221], v[0:3]
	v_mfma_f32_16x16x32_bf16 v[52:55], v[182:185], v[198:201], v[52:55]
	v_mfma_f32_16x16x32_bf16 v[44:47], v[190:193], v[198:201], v[44:47]
	v_mfma_f32_16x16x32_bf16 v[36:39], v[182:185], v[206:209], v[36:39]
	v_mfma_f32_16x16x32_bf16 v[28:31], v[190:193], v[206:209], v[28:31]
	v_mfma_f32_16x16x32_bf16 v[20:23], v[182:185], v[214:217], v[20:23]
	v_mfma_f32_16x16x32_bf16 v[12:15], v[190:193], v[214:217], v[12:15]
	v_mfma_f32_16x16x32_bf16 v[4:7], v[182:185], v[222:225], v[4:7]
	v_mfma_f32_16x16x32_bf16 v[0:3], v[190:193], v[222:225], v[0:3]
	s_barrier
	s_add_i32 s49, s49, 2
	s_add_u32 s20, s20, 0x100
	s_addc_u32 s21, s21, 0
	s_add_u32 s47, s47, 0x100
	s_addc_u32 s48, s48, 0
	s_cmp_gt_u32 s49, 13
	s_branch .LBB0_184

.LBB0_241:
	s_add_i32 s39, s10, 2
	s_add_u32 s40, s8, 0x80
	s_addc_u32 s11, s9, 0
	s_add_i32 s42, 0, 0x10000
	s_cmp_eq_u32 s13, s10
	s_cselect_b32 s11, s93, s11
	s_cselect_b32 s10, s92, s40
	v_add_u32_e32 v156, s42, v170
	s_cselect_b32 s41, s95, s25
	s_cselect_b32 s40, s94, s24
	s_add_i32 s43, 0, 0x14000
	ds_read_b128 v[148:151], v156
	ds_read_b128 v[152:155], v156 offset:1024
	ds_read_b128 v[174:177], v156 offset:2048
	ds_read_b128 v[178:181], v156 offset:3072
	v_add_u32_e32 v156, s43, v170
	ds_read_b128 v[182:185], v156
	ds_read_b128 v[186:189], v156 offset:1024
	ds_read_b128 v[190:193], v156 offset:2048
	ds_read_b128 v[194:197], v156 offset:3072
	v_lshl_add_u64 v[156:157], s[8:9], 0, v[146:147]
	s_add_i32 m0, s98, 0xc000
	ds_read_b128 v[198:201], v172
	ds_read_b128 v[202:205], v172 offset:1024
	ds_read_b128 v[206:209], v172 offset:2048
	ds_read_b128 v[210:213], v172 offset:3072
	ds_read_b128 v[214:217], v172 offset:4096
	ds_read_b128 v[218:221], v172 offset:5120
	ds_read_b128 v[222:225], v172 offset:6144
	ds_read_b128 v[226:229], v172 offset:7168
	global_load_lds_dwordx4 v[156:157], off
	v_lshl_add_u64 v[156:157], s[8:9], 0, v[144:145]
	s_add_i32 m0, s98, 0xe000
	s_nop 0
	global_load_lds_dwordx4 v[156:157], off
	s_waitcnt vmcnt(8)
	s_waitcnt lgkmcnt(0)
	s_barrier
	s_waitcnt lgkmcnt(0)
	v_mfma_f32_16x16x32_bf16 v[124:127], v[148:151], v[198:201], v[124:127]
	v_mfma_f32_16x16x32_bf16 v[120:123], v[174:177], v[198:201], v[120:123]
	v_mfma_f32_16x16x32_bf16 v[108:111], v[148:151], v[206:209], v[108:111]
	v_mfma_f32_16x16x32_bf16 v[104:107], v[174:177], v[206:209], v[104:107]
	v_mfma_f32_16x16x32_bf16 v[92:95], v[148:151], v[214:217], v[92:95]
	v_mfma_f32_16x16x32_bf16 v[88:91], v[174:177], v[214:217], v[88:91]
	v_mfma_f32_16x16x32_bf16 v[76:79], v[148:151], v[222:225], v[76:79]
	v_mfma_f32_16x16x32_bf16 v[72:75], v[174:177], v[222:225], v[72:75]
	v_mfma_f32_16x16x32_bf16 v[124:127], v[152:155], v[202:205], v[124:127]
	v_mfma_f32_16x16x32_bf16 v[120:123], v[178:181], v[202:205], v[120:123]
	v_mfma_f32_16x16x32_bf16 v[108:111], v[152:155], v[210:213], v[108:111]
	v_mfma_f32_16x16x32_bf16 v[104:107], v[178:181], v[210:213], v[104:107]
	v_mfma_f32_16x16x32_bf16 v[92:95], v[152:155], v[218:221], v[92:95]
	v_mfma_f32_16x16x32_bf16 v[88:91], v[178:181], v[218:221], v[88:91]
	v_mfma_f32_16x16x32_bf16 v[76:79], v[152:155], v[226:229], v[76:79]
	v_mfma_f32_16x16x32_bf16 v[72:75], v[178:181], v[226:229], v[72:75]
	v_mfma_f32_16x16x32_bf16 v[116:119], v[182:185], v[198:201], v[116:119]
	v_mfma_f32_16x16x32_bf16 v[112:115], v[190:193], v[198:201], v[112:115]
	v_mfma_f32_16x16x32_bf16 v[100:103], v[182:185], v[206:209], v[100:103]
	v_mfma_f32_16x16x32_bf16 v[96:99], v[190:193], v[206:209], v[96:99]
	v_mfma_f32_16x16x32_bf16 v[84:87], v[182:185], v[214:217], v[84:87]
	v_mfma_f32_16x16x32_bf16 v[80:83], v[190:193], v[214:217], v[80:83]
	v_mfma_f32_16x16x32_bf16 v[68:71], v[182:185], v[222:225], v[68:71]
	v_mfma_f32_16x16x32_bf16 v[64:67], v[190:193], v[222:225], v[64:67]
	v_mfma_f32_16x16x32_bf16 v[116:119], v[186:189], v[202:205], v[116:119]
	v_mfma_f32_16x16x32_bf16 v[112:115], v[194:197], v[202:205], v[112:115]
	v_mfma_f32_16x16x32_bf16 v[100:103], v[186:189], v[210:213], v[100:103]
	v_mfma_f32_16x16x32_bf16 v[96:99], v[194:197], v[210:213], v[96:99]
	v_mfma_f32_16x16x32_bf16 v[84:87], v[186:189], v[218:221], v[84:87]
	v_mfma_f32_16x16x32_bf16 v[80:83], v[194:197], v[218:221], v[80:83]
	v_mfma_f32_16x16x32_bf16 v[68:71], v[186:189], v[226:229], v[68:71]
	v_mfma_f32_16x16x32_bf16 v[64:67], v[194:197], v[226:229], v[64:67]
	s_barrier
	s_add_i32 s42, s42, s81
	v_lshl_add_u64 v[156:157], s[40:41], 0, v[128:129]
	s_mov_b32 m0, s42
	ds_read_b128 v[198:201], v172 offset:16384
	ds_read_b128 v[202:205], v172 offset:17408
	ds_read_b128 v[206:209], v172 offset:18432
	ds_read_b128 v[210:213], v172 offset:19456
	ds_read_b128 v[214:217], v172 offset:20480
	ds_read_b128 v[218:221], v172 offset:21504
	ds_read_b128 v[222:225], v172 offset:22528
	ds_read_b128 v[226:229], v172 offset:23552
	global_load_lds_dwordx4 v[156:157], off
	s_add_i32 m0, s42, 0x2000
	v_lshl_add_u64 v[230:231], s[40:41], 0, v[138:139]
	s_add_u32 s40, s40, s0
	s_addc_u32 s41, s41, 0
	s_add_i32 s42, s43, s81
	global_load_lds_dwordx4 v[230:231], off
	v_lshl_add_u64 v[232:233], s[40:41], 0, v[128:129]
	s_mov_b32 m0, s42
	v_lshl_add_u64 v[234:235], s[40:41], 0, v[138:139]
	global_load_lds_dwordx4 v[232:233], off
	s_add_i32 m0, s42, 0x2000
	v_lshl_add_u64 v[236:237], s[10:11], 0, v[134:135]
	global_load_lds_dwordx4 v[234:235], off
	s_mov_b32 m0, s98
	v_lshl_add_u64 v[238:239], s[10:11], 0, v[136:137]
	global_load_lds_dwordx4 v[236:237], off
	s_mov_b32 m0, s99
	s_nop 0
	global_load_lds_dwordx4 v[238:239], off
	s_waitcnt vmcnt(8)
	s_waitcnt lgkmcnt(0)
	s_barrier
	s_waitcnt lgkmcnt(0)
	v_mfma_f32_16x16x32_bf16 v[60:63], v[148:151], v[198:201], v[60:63]
	v_mfma_f32_16x16x32_bf16 v[56:59], v[174:177], v[198:201], v[56:59]
	v_mfma_f32_16x16x32_bf16 v[44:47], v[148:151], v[206:209], v[44:47]
	v_mfma_f32_16x16x32_bf16 v[40:43], v[174:177], v[206:209], v[40:43]
	v_mfma_f32_16x16x32_bf16 v[28:31], v[148:151], v[214:217], v[28:31]
	v_mfma_f32_16x16x32_bf16 v[24:27], v[174:177], v[214:217], v[24:27]
	v_mfma_f32_16x16x32_bf16 v[12:15], v[148:151], v[222:225], v[12:15]
	v_mfma_f32_16x16x32_bf16 v[8:11], v[174:177], v[222:225], v[8:11]
	v_mfma_f32_16x16x32_bf16 v[60:63], v[152:155], v[202:205], v[60:63]
	v_mfma_f32_16x16x32_bf16 v[56:59], v[178:181], v[202:205], v[56:59]
	v_mfma_f32_16x16x32_bf16 v[44:47], v[152:155], v[210:213], v[44:47]
	v_mfma_f32_16x16x32_bf16 v[40:43], v[178:181], v[210:213], v[40:43]
	v_mfma_f32_16x16x32_bf16 v[28:31], v[152:155], v[218:221], v[28:31]
	v_mfma_f32_16x16x32_bf16 v[24:27], v[178:181], v[218:221], v[24:27]
	v_mfma_f32_16x16x32_bf16 v[12:15], v[152:155], v[226:229], v[12:15]
	v_mfma_f32_16x16x32_bf16 v[8:11], v[178:181], v[226:229], v[8:11]
	v_mfma_f32_16x16x32_bf16 v[52:55], v[182:185], v[198:201], v[52:55]
	v_mfma_f32_16x16x32_bf16 v[48:51], v[190:193], v[198:201], v[48:51]
	v_mfma_f32_16x16x32_bf16 v[36:39], v[182:185], v[206:209], v[36:39]
	v_mfma_f32_16x16x32_bf16 v[32:35], v[190:193], v[206:209], v[32:35]
	v_mfma_f32_16x16x32_bf16 v[20:23], v[182:185], v[214:217], v[20:23]
	v_mfma_f32_16x16x32_bf16 v[16:19], v[190:193], v[214:217], v[16:19]
	v_mfma_f32_16x16x32_bf16 v[0:3], v[182:185], v[222:225], v[0:3]
	v_mfma_f32_16x16x32_bf16 v[4:7], v[190:193], v[222:225], v[4:7]
	v_mfma_f32_16x16x32_bf16 v[52:55], v[186:189], v[202:205], v[52:55]
	v_mfma_f32_16x16x32_bf16 v[48:51], v[194:197], v[202:205], v[48:51]
	v_mfma_f32_16x16x32_bf16 v[36:39], v[186:189], v[210:213], v[36:39]
	v_mfma_f32_16x16x32_bf16 v[32:35], v[194:197], v[210:213], v[32:35]
	v_mfma_f32_16x16x32_bf16 v[20:23], v[186:189], v[218:221], v[20:23]
	v_mfma_f32_16x16x32_bf16 v[16:19], v[194:197], v[218:221], v[16:19]
	v_mfma_f32_16x16x32_bf16 v[0:3], v[186:189], v[226:229], v[0:3]
	v_mfma_f32_16x16x32_bf16 v[4:7], v[194:197], v[226:229], v[4:7]
	s_barrier
	s_add_i32 s40, 0, 0x18000
	v_add_u32_e32 v173, s40, v170
	s_add_i32 s41, 0, 0x1c000
	ds_read_b128 v[148:151], v173
	ds_read_b128 v[152:155], v173 offset:1024
	ds_read_b128 v[174:177], v173 offset:2048
	ds_read_b128 v[178:181], v173 offset:3072
	v_add_u32_e32 v173, s41, v170
	ds_read_b128 v[182:185], v173
	ds_read_b128 v[186:189], v173 offset:1024
	ds_read_b128 v[190:193], v173 offset:2048
	ds_read_b128 v[194:197], v173 offset:3072
	s_add_u32 s10, s10, s0
	s_addc_u32 s11, s11, 0
	s_mov_b32 m0, s77
	v_lshl_add_u64 v[240:241], s[10:11], 0, v[134:135]
	ds_read_b128 v[198:201], v172 offset:32768
	ds_read_b128 v[202:205], v172 offset:33792
	ds_read_b128 v[206:209], v172 offset:34816
	ds_read_b128 v[210:213], v172 offset:35840
	ds_read_b128 v[214:217], v172 offset:36864
	ds_read_b128 v[218:221], v172 offset:37888
	ds_read_b128 v[222:225], v172 offset:38912
	ds_read_b128 v[226:229], v172 offset:39936
	global_load_lds_dwordx4 v[240:241], off
	v_lshl_add_u64 v[240:241], s[10:11], 0, v[136:137]
	s_mov_b32 m0, s78
	s_nop 0
	global_load_lds_dwordx4 v[240:241], off
	s_waitcnt vmcnt(8)
	s_waitcnt lgkmcnt(0)
	s_barrier
	s_waitcnt lgkmcnt(0)
	v_mfma_f32_16x16x32_bf16 v[124:127], v[148:151], v[198:201], v[124:127]
	v_mfma_f32_16x16x32_bf16 v[120:123], v[174:177], v[198:201], v[120:123]
	v_mfma_f32_16x16x32_bf16 v[108:111], v[148:151], v[206:209], v[108:111]
	v_mfma_f32_16x16x32_bf16 v[104:107], v[174:177], v[206:209], v[104:107]
	v_mfma_f32_16x16x32_bf16 v[92:95], v[148:151], v[214:217], v[92:95]
	v_mfma_f32_16x16x32_bf16 v[88:91], v[174:177], v[214:217], v[88:91]
	v_mfma_f32_16x16x32_bf16 v[76:79], v[148:151], v[222:225], v[76:79]
	v_mfma_f32_16x16x32_bf16 v[72:75], v[174:177], v[222:225], v[72:75]
	v_mfma_f32_16x16x32_bf16 v[124:127], v[152:155], v[202:205], v[124:127]
	v_mfma_f32_16x16x32_bf16 v[120:123], v[178:181], v[202:205], v[120:123]
	v_mfma_f32_16x16x32_bf16 v[108:111], v[152:155], v[210:213], v[108:111]
	v_mfma_f32_16x16x32_bf16 v[104:107], v[178:181], v[210:213], v[104:107]
	v_mfma_f32_16x16x32_bf16 v[92:95], v[152:155], v[218:221], v[92:95]
	v_mfma_f32_16x16x32_bf16 v[88:91], v[178:181], v[218:221], v[88:91]
	v_mfma_f32_16x16x32_bf16 v[76:79], v[152:155], v[226:229], v[76:79]
	v_mfma_f32_16x16x32_bf16 v[72:75], v[178:181], v[226:229], v[72:75]
	v_mfma_f32_16x16x32_bf16 v[116:119], v[182:185], v[198:201], v[116:119]
	v_mfma_f32_16x16x32_bf16 v[112:115], v[190:193], v[198:201], v[112:115]
	v_mfma_f32_16x16x32_bf16 v[100:103], v[182:185], v[206:209], v[100:103]
	v_mfma_f32_16x16x32_bf16 v[96:99], v[190:193], v[206:209], v[96:99]
	v_mfma_f32_16x16x32_bf16 v[84:87], v[182:185], v[214:217], v[84:87]
	v_mfma_f32_16x16x32_bf16 v[80:83], v[190:193], v[214:217], v[80:83]
	v_mfma_f32_16x16x32_bf16 v[68:71], v[182:185], v[222:225], v[68:71]
	v_mfma_f32_16x16x32_bf16 v[64:67], v[190:193], v[222:225], v[64:67]
	v_mfma_f32_16x16x32_bf16 v[116:119], v[186:189], v[202:205], v[116:119]
	v_mfma_f32_16x16x32_bf16 v[112:115], v[194:197], v[202:205], v[112:115]
	v_mfma_f32_16x16x32_bf16 v[100:103], v[186:189], v[210:213], v[100:103]
	v_mfma_f32_16x16x32_bf16 v[96:99], v[194:197], v[210:213], v[96:99]
	v_mfma_f32_16x16x32_bf16 v[84:87], v[186:189], v[218:221], v[84:87]
	v_mfma_f32_16x16x32_bf16 v[80:83], v[194:197], v[218:221], v[80:83]
	v_mfma_f32_16x16x32_bf16 v[68:71], v[186:189], v[226:229], v[68:71]
	v_mfma_f32_16x16x32_bf16 v[64:67], v[194:197], v[226:229], v[64:67]
	s_barrier
	s_add_i32 s10, s40, s81
	v_lshl_add_u64 v[156:157], v[156:157], 0, s[84:85]
	s_mov_b32 m0, s10
	ds_read_b128 v[198:201], v172 offset:49152
	ds_read_b128 v[202:205], v172 offset:50176
	ds_read_b128 v[206:209], v172 offset:51200
	ds_read_b128 v[210:213], v172 offset:52224
	ds_read_b128 v[214:217], v172 offset:53248
	ds_read_b128 v[218:221], v172 offset:54272
	ds_read_b128 v[222:225], v172 offset:55296
	ds_read_b128 v[226:229], v172 offset:56320
	global_load_lds_dwordx4 v[156:157], off
	v_lshl_add_u64 v[156:157], v[230:231], 0, s[84:85]
	s_add_i32 m0, s10, 0x2000
	s_add_i32 s10, s41, s81
	global_load_lds_dwordx4 v[156:157], off
	v_lshl_add_u64 v[156:157], v[232:233], 0, s[84:85]
	s_mov_b32 m0, s10
	s_nop 0
	global_load_lds_dwordx4 v[156:157], off
	v_lshl_add_u64 v[156:157], v[234:235], 0, s[84:85]
	s_add_i32 m0, s10, 0x2000
	s_nop 0
	global_load_lds_dwordx4 v[156:157], off
	v_lshl_add_u64 v[156:157], v[236:237], 0, s[84:85]
	s_mov_b32 m0, s79
	s_nop 0
	global_load_lds_dwordx4 v[156:157], off
	v_lshl_add_u64 v[156:157], v[238:239], 0, s[84:85]
	s_mov_b32 m0, s90
	s_nop 0
	global_load_lds_dwordx4 v[156:157], off
	s_waitcnt vmcnt(8)
	s_waitcnt lgkmcnt(0)
	s_barrier
	s_waitcnt lgkmcnt(0)
	v_mfma_f32_16x16x32_bf16 v[60:63], v[148:151], v[198:201], v[60:63]
	v_mfma_f32_16x16x32_bf16 v[56:59], v[174:177], v[198:201], v[56:59]
	v_mfma_f32_16x16x32_bf16 v[44:47], v[148:151], v[206:209], v[44:47]
	v_mfma_f32_16x16x32_bf16 v[40:43], v[174:177], v[206:209], v[40:43]
	v_mfma_f32_16x16x32_bf16 v[28:31], v[148:151], v[214:217], v[28:31]
	v_mfma_f32_16x16x32_bf16 v[24:27], v[174:177], v[214:217], v[24:27]
	v_mfma_f32_16x16x32_bf16 v[12:15], v[148:151], v[222:225], v[12:15]
	v_mfma_f32_16x16x32_bf16 v[8:11], v[174:177], v[222:225], v[8:11]
	v_mfma_f32_16x16x32_bf16 v[60:63], v[152:155], v[202:205], v[60:63]
	v_mfma_f32_16x16x32_bf16 v[56:59], v[178:181], v[202:205], v[56:59]
	v_mfma_f32_16x16x32_bf16 v[44:47], v[152:155], v[210:213], v[44:47]
	v_mfma_f32_16x16x32_bf16 v[40:43], v[178:181], v[210:213], v[40:43]
	v_mfma_f32_16x16x32_bf16 v[28:31], v[152:155], v[218:221], v[28:31]
	v_mfma_f32_16x16x32_bf16 v[24:27], v[178:181], v[218:221], v[24:27]
	v_mfma_f32_16x16x32_bf16 v[12:15], v[152:155], v[226:229], v[12:15]
	v_mfma_f32_16x16x32_bf16 v[8:11], v[178:181], v[226:229], v[8:11]
	v_mfma_f32_16x16x32_bf16 v[52:55], v[182:185], v[198:201], v[52:55]
	v_mfma_f32_16x16x32_bf16 v[48:51], v[190:193], v[198:201], v[48:51]
	v_mfma_f32_16x16x32_bf16 v[36:39], v[182:185], v[206:209], v[36:39]
	v_mfma_f32_16x16x32_bf16 v[32:35], v[190:193], v[206:209], v[32:35]
	v_mfma_f32_16x16x32_bf16 v[20:23], v[182:185], v[214:217], v[20:23]
	v_mfma_f32_16x16x32_bf16 v[16:19], v[190:193], v[214:217], v[16:19]
	v_mfma_f32_16x16x32_bf16 v[0:3], v[182:185], v[222:225], v[0:3]
	v_mfma_f32_16x16x32_bf16 v[4:7], v[190:193], v[222:225], v[4:7]
	v_mfma_f32_16x16x32_bf16 v[52:55], v[186:189], v[202:205], v[52:55]
	v_mfma_f32_16x16x32_bf16 v[48:51], v[194:197], v[202:205], v[48:51]
	v_mfma_f32_16x16x32_bf16 v[36:39], v[186:189], v[210:213], v[36:39]
	v_mfma_f32_16x16x32_bf16 v[32:35], v[194:197], v[210:213], v[32:35]
	v_mfma_f32_16x16x32_bf16 v[20:23], v[186:189], v[218:221], v[20:23]
	v_mfma_f32_16x16x32_bf16 v[16:19], v[194:197], v[218:221], v[16:19]
	v_mfma_f32_16x16x32_bf16 v[0:3], v[186:189], v[226:229], v[0:3]
	v_mfma_f32_16x16x32_bf16 v[4:7], v[194:197], v[226:229], v[4:7]
	s_barrier
	s_add_u32 s24, s24, 0x100
	s_addc_u32 s25, s25, 0
	s_add_u32 s8, s8, 0x100
	s_addc_u32 s9, s9, 0
	s_cmp_ge_u32 s39, s26
	s_mov_b32 s10, s39
	s_cbranch_scc0 .LBB0_241
	s_branch .Lit0_res_skip
.Lit0_res:
	s_add_i32 s39, s10, 2
	s_add_u32 s40, s8, 0x80
	s_addc_u32 s11, s9, 0
	s_add_i32 s42, 0, 0x10000
	s_cmp_eq_u32 s13, s10
	s_cselect_b32 s11, s93, s11
	s_cselect_b32 s10, s92, s40
	v_add_u32_e32 v156, s42, v170
	s_cselect_b32 s41, s95, s25
	s_cselect_b32 s40, s94, s24
	s_add_i32 s43, 0, 0x14000
	ds_read_b128 v[148:151], v156
	ds_read_b128 v[152:155], v156 offset:1024
	ds_read_b128 v[174:177], v156 offset:2048
	ds_read_b128 v[178:181], v156 offset:3072
	v_add_u32_e32 v156, s43, v170
	ds_read_b128 v[182:185], v156
	ds_read_b128 v[186:189], v156 offset:1024
	ds_read_b128 v[190:193], v156 offset:2048
	ds_read_b128 v[194:197], v156 offset:3072
	v_lshl_add_u64 v[156:157], s[8:9], 0, v[146:147]
	s_add_i32 m0, s98, 0xc000
	ds_read_b128 v[198:201], v172
	ds_read_b128 v[202:205], v172 offset:1024
	ds_read_b128 v[206:209], v172 offset:2048
	ds_read_b128 v[210:213], v172 offset:3072
	ds_read_b128 v[214:217], v172 offset:4096
	ds_read_b128 v[218:221], v172 offset:5120
	ds_read_b128 v[222:225], v172 offset:6144
	ds_read_b128 v[226:229], v172 offset:7168
	global_load_lds_dwordx4 v[156:157], off
	v_lshl_add_u64 v[156:157], s[8:9], 0, v[144:145]
	s_add_i32 m0, s98, 0xe000
	s_nop 0
	global_load_lds_dwordx4 v[156:157], off
	s_waitcnt vmcnt(8)
	s_waitcnt lgkmcnt(0)
	s_barrier
	s_waitcnt lgkmcnt(0)
	v_mfma_f32_16x16x32_bf16 v[124:127], v[148:151], v[198:201], 0
	v_mfma_f32_16x16x32_bf16 v[120:123], v[174:177], v[198:201], 0
	v_mfma_f32_16x16x32_bf16 v[108:111], v[148:151], v[206:209], 0
	v_mfma_f32_16x16x32_bf16 v[104:107], v[174:177], v[206:209], 0
	v_mfma_f32_16x16x32_bf16 v[92:95], v[148:151], v[214:217], 0
	v_mfma_f32_16x16x32_bf16 v[88:91], v[174:177], v[214:217], 0
	v_mfma_f32_16x16x32_bf16 v[76:79], v[148:151], v[222:225], 0
	v_mfma_f32_16x16x32_bf16 v[72:75], v[174:177], v[222:225], 0
	v_mfma_f32_16x16x32_bf16 v[124:127], v[152:155], v[202:205], v[124:127]
	v_mfma_f32_16x16x32_bf16 v[120:123], v[178:181], v[202:205], v[120:123]
	v_mfma_f32_16x16x32_bf16 v[108:111], v[152:155], v[210:213], v[108:111]
	v_mfma_f32_16x16x32_bf16 v[104:107], v[178:181], v[210:213], v[104:107]
	v_mfma_f32_16x16x32_bf16 v[92:95], v[152:155], v[218:221], v[92:95]
	v_mfma_f32_16x16x32_bf16 v[88:91], v[178:181], v[218:221], v[88:91]
	v_mfma_f32_16x16x32_bf16 v[76:79], v[152:155], v[226:229], v[76:79]
	v_mfma_f32_16x16x32_bf16 v[72:75], v[178:181], v[226:229], v[72:75]
	v_mfma_f32_16x16x32_bf16 v[116:119], v[182:185], v[198:201], 0
	v_mfma_f32_16x16x32_bf16 v[112:115], v[190:193], v[198:201], 0
	v_mfma_f32_16x16x32_bf16 v[100:103], v[182:185], v[206:209], 0
	v_mfma_f32_16x16x32_bf16 v[96:99], v[190:193], v[206:209], 0
	v_mfma_f32_16x16x32_bf16 v[84:87], v[182:185], v[214:217], 0
	v_mfma_f32_16x16x32_bf16 v[80:83], v[190:193], v[214:217], 0
	v_mfma_f32_16x16x32_bf16 v[68:71], v[182:185], v[222:225], 0
	v_mfma_f32_16x16x32_bf16 v[64:67], v[190:193], v[222:225], 0
	v_mfma_f32_16x16x32_bf16 v[116:119], v[186:189], v[202:205], v[116:119]
	v_mfma_f32_16x16x32_bf16 v[112:115], v[194:197], v[202:205], v[112:115]
	v_mfma_f32_16x16x32_bf16 v[100:103], v[186:189], v[210:213], v[100:103]
	v_mfma_f32_16x16x32_bf16 v[96:99], v[194:197], v[210:213], v[96:99]
	v_mfma_f32_16x16x32_bf16 v[84:87], v[186:189], v[218:221], v[84:87]
	v_mfma_f32_16x16x32_bf16 v[80:83], v[194:197], v[218:221], v[80:83]
	v_mfma_f32_16x16x32_bf16 v[68:71], v[186:189], v[226:229], v[68:71]
	v_mfma_f32_16x16x32_bf16 v[64:67], v[194:197], v[226:229], v[64:67]
	s_barrier
	s_add_i32 s42, s42, s81
	v_lshl_add_u64 v[156:157], s[40:41], 0, v[128:129]
	s_mov_b32 m0, s42
	ds_read_b128 v[198:201], v172 offset:16384
	ds_read_b128 v[202:205], v172 offset:17408
	ds_read_b128 v[206:209], v172 offset:18432
	ds_read_b128 v[210:213], v172 offset:19456
	ds_read_b128 v[214:217], v172 offset:20480
	ds_read_b128 v[218:221], v172 offset:21504
	ds_read_b128 v[222:225], v172 offset:22528
	ds_read_b128 v[226:229], v172 offset:23552
	global_load_lds_dwordx4 v[156:157], off
	s_add_i32 m0, s42, 0x2000
	v_lshl_add_u64 v[230:231], s[40:41], 0, v[138:139]
	s_add_u32 s40, s40, s0
	s_addc_u32 s41, s41, 0
	s_add_i32 s42, s43, s81
	global_load_lds_dwordx4 v[230:231], off
	v_lshl_add_u64 v[232:233], s[40:41], 0, v[128:129]
	s_mov_b32 m0, s42
	v_lshl_add_u64 v[234:235], s[40:41], 0, v[138:139]
	global_load_lds_dwordx4 v[232:233], off
	s_add_i32 m0, s42, 0x2000
	v_lshl_add_u64 v[236:237], s[10:11], 0, v[134:135]
	global_load_lds_dwordx4 v[234:235], off
	s_mov_b32 m0, s98
	v_lshl_add_u64 v[238:239], s[10:11], 0, v[136:137]
	global_load_lds_dwordx4 v[236:237], off
	s_mov_b32 m0, s99
	s_nop 0
	global_load_lds_dwordx4 v[238:239], off
	s_waitcnt vmcnt(8)
	s_waitcnt lgkmcnt(0)
	s_barrier
	s_waitcnt lgkmcnt(0)
	v_mfma_f32_16x16x32_bf16 v[60:63], v[148:151], v[198:201], 0
	v_mfma_f32_16x16x32_bf16 v[56:59], v[174:177], v[198:201], 0
	v_mfma_f32_16x16x32_bf16 v[44:47], v[148:151], v[206:209], 0
	v_mfma_f32_16x16x32_bf16 v[40:43], v[174:177], v[206:209], 0
	v_mfma_f32_16x16x32_bf16 v[28:31], v[148:151], v[214:217], 0
	v_mfma_f32_16x16x32_bf16 v[24:27], v[174:177], v[214:217], 0
	v_mfma_f32_16x16x32_bf16 v[12:15], v[148:151], v[222:225], 0
	v_mfma_f32_16x16x32_bf16 v[8:11], v[174:177], v[222:225], 0
	v_mfma_f32_16x16x32_bf16 v[60:63], v[152:155], v[202:205], v[60:63]
	v_mfma_f32_16x16x32_bf16 v[56:59], v[178:181], v[202:205], v[56:59]
	v_mfma_f32_16x16x32_bf16 v[44:47], v[152:155], v[210:213], v[44:47]
	v_mfma_f32_16x16x32_bf16 v[40:43], v[178:181], v[210:213], v[40:43]
	v_mfma_f32_16x16x32_bf16 v[28:31], v[152:155], v[218:221], v[28:31]
	v_mfma_f32_16x16x32_bf16 v[24:27], v[178:181], v[218:221], v[24:27]
	v_mfma_f32_16x16x32_bf16 v[12:15], v[152:155], v[226:229], v[12:15]
	v_mfma_f32_16x16x32_bf16 v[8:11], v[178:181], v[226:229], v[8:11]
	v_mfma_f32_16x16x32_bf16 v[52:55], v[182:185], v[198:201], 0
	v_mfma_f32_16x16x32_bf16 v[48:51], v[190:193], v[198:201], 0
	v_mfma_f32_16x16x32_bf16 v[36:39], v[182:185], v[206:209], 0
	v_mfma_f32_16x16x32_bf16 v[32:35], v[190:193], v[206:209], 0
	v_mfma_f32_16x16x32_bf16 v[20:23], v[182:185], v[214:217], 0
	v_mfma_f32_16x16x32_bf16 v[16:19], v[190:193], v[214:217], 0
	v_mfma_f32_16x16x32_bf16 v[0:3], v[182:185], v[222:225], 0
	v_mfma_f32_16x16x32_bf16 v[4:7], v[190:193], v[222:225], 0
	v_mfma_f32_16x16x32_bf16 v[52:55], v[186:189], v[202:205], v[52:55]
	v_mfma_f32_16x16x32_bf16 v[48:51], v[194:197], v[202:205], v[48:51]
	v_mfma_f32_16x16x32_bf16 v[36:39], v[186:189], v[210:213], v[36:39]
	v_mfma_f32_16x16x32_bf16 v[32:35], v[194:197], v[210:213], v[32:35]
	v_mfma_f32_16x16x32_bf16 v[20:23], v[186:189], v[218:221], v[20:23]
	v_mfma_f32_16x16x32_bf16 v[16:19], v[194:197], v[218:221], v[16:19]
	v_mfma_f32_16x16x32_bf16 v[0:3], v[186:189], v[226:229], v[0:3]
	v_mfma_f32_16x16x32_bf16 v[4:7], v[194:197], v[226:229], v[4:7]
	s_barrier
	s_add_i32 s40, 0, 0x18000
	v_add_u32_e32 v173, s40, v170
	s_add_i32 s41, 0, 0x1c000
	ds_read_b128 v[148:151], v173
	ds_read_b128 v[152:155], v173 offset:1024
	ds_read_b128 v[174:177], v173 offset:2048
	ds_read_b128 v[178:181], v173 offset:3072
	v_add_u32_e32 v173, s41, v170
	ds_read_b128 v[182:185], v173
	ds_read_b128 v[186:189], v173 offset:1024
	ds_read_b128 v[190:193], v173 offset:2048
	ds_read_b128 v[194:197], v173 offset:3072
	s_add_u32 s10, s10, s0
	s_addc_u32 s11, s11, 0
	s_mov_b32 m0, s77
	v_lshl_add_u64 v[240:241], s[10:11], 0, v[134:135]
	ds_read_b128 v[198:201], v172 offset:32768
	ds_read_b128 v[202:205], v172 offset:33792
	ds_read_b128 v[206:209], v172 offset:34816
	ds_read_b128 v[210:213], v172 offset:35840
	ds_read_b128 v[214:217], v172 offset:36864
	ds_read_b128 v[218:221], v172 offset:37888
	ds_read_b128 v[222:225], v172 offset:38912
	ds_read_b128 v[226:229], v172 offset:39936
	global_load_lds_dwordx4 v[240:241], off
	v_lshl_add_u64 v[240:241], s[10:11], 0, v[136:137]
	s_mov_b32 m0, s78
	s_nop 0
	global_load_lds_dwordx4 v[240:241], off
	s_waitcnt vmcnt(8)
	s_waitcnt lgkmcnt(0)
	s_barrier
	s_waitcnt lgkmcnt(0)
	v_mfma_f32_16x16x32_bf16 v[124:127], v[148:151], v[198:201], v[124:127]
	v_mfma_f32_16x16x32_bf16 v[120:123], v[174:177], v[198:201], v[120:123]
	v_mfma_f32_16x16x32_bf16 v[108:111], v[148:151], v[206:209], v[108:111]
	v_mfma_f32_16x16x32_bf16 v[104:107], v[174:177], v[206:209], v[104:107]
	v_mfma_f32_16x16x32_bf16 v[92:95], v[148:151], v[214:217], v[92:95]
	v_mfma_f32_16x16x32_bf16 v[88:91], v[174:177], v[214:217], v[88:91]
	v_mfma_f32_16x16x32_bf16 v[76:79], v[148:151], v[222:225], v[76:79]
	v_mfma_f32_16x16x32_bf16 v[72:75], v[174:177], v[222:225], v[72:75]
	v_mfma_f32_16x16x32_bf16 v[124:127], v[152:155], v[202:205], v[124:127]
	v_mfma_f32_16x16x32_bf16 v[120:123], v[178:181], v[202:205], v[120:123]
	v_mfma_f32_16x16x32_bf16 v[108:111], v[152:155], v[210:213], v[108:111]
	v_mfma_f32_16x16x32_bf16 v[104:107], v[178:181], v[210:213], v[104:107]
	v_mfma_f32_16x16x32_bf16 v[92:95], v[152:155], v[218:221], v[92:95]
	v_mfma_f32_16x16x32_bf16 v[88:91], v[178:181], v[218:221], v[88:91]
	v_mfma_f32_16x16x32_bf16 v[76:79], v[152:155], v[226:229], v[76:79]
	v_mfma_f32_16x16x32_bf16 v[72:75], v[178:181], v[226:229], v[72:75]
	v_mfma_f32_16x16x32_bf16 v[116:119], v[182:185], v[198:201], v[116:119]
	v_mfma_f32_16x16x32_bf16 v[112:115], v[190:193], v[198:201], v[112:115]
	v_mfma_f32_16x16x32_bf16 v[100:103], v[182:185], v[206:209], v[100:103]
	v_mfma_f32_16x16x32_bf16 v[96:99], v[190:193], v[206:209], v[96:99]
	v_mfma_f32_16x16x32_bf16 v[84:87], v[182:185], v[214:217], v[84:87]
	v_mfma_f32_16x16x32_bf16 v[80:83], v[190:193], v[214:217], v[80:83]
	v_mfma_f32_16x16x32_bf16 v[68:71], v[182:185], v[222:225], v[68:71]
	v_mfma_f32_16x16x32_bf16 v[64:67], v[190:193], v[222:225], v[64:67]
	v_mfma_f32_16x16x32_bf16 v[116:119], v[186:189], v[202:205], v[116:119]
	v_mfma_f32_16x16x32_bf16 v[112:115], v[194:197], v[202:205], v[112:115]
	v_mfma_f32_16x16x32_bf16 v[100:103], v[186:189], v[210:213], v[100:103]
	v_mfma_f32_16x16x32_bf16 v[96:99], v[194:197], v[210:213], v[96:99]
	v_mfma_f32_16x16x32_bf16 v[84:87], v[186:189], v[218:221], v[84:87]
	v_mfma_f32_16x16x32_bf16 v[80:83], v[194:197], v[218:221], v[80:83]
	v_mfma_f32_16x16x32_bf16 v[68:71], v[186:189], v[226:229], v[68:71]
	v_mfma_f32_16x16x32_bf16 v[64:67], v[194:197], v[226:229], v[64:67]
	s_barrier
	s_add_i32 s10, s40, s81
	v_lshl_add_u64 v[156:157], v[156:157], 0, s[84:85]
	s_mov_b32 m0, s10
	ds_read_b128 v[198:201], v172 offset:49152
	ds_read_b128 v[202:205], v172 offset:50176
	ds_read_b128 v[206:209], v172 offset:51200
	ds_read_b128 v[210:213], v172 offset:52224
	ds_read_b128 v[214:217], v172 offset:53248
	ds_read_b128 v[218:221], v172 offset:54272
	ds_read_b128 v[222:225], v172 offset:55296
	ds_read_b128 v[226:229], v172 offset:56320
	global_load_lds_dwordx4 v[156:157], off
	v_lshl_add_u64 v[156:157], v[230:231], 0, s[84:85]
	s_add_i32 m0, s10, 0x2000
	s_add_i32 s10, s41, s81
	global_load_lds_dwordx4 v[156:157], off
	v_lshl_add_u64 v[156:157], v[232:233], 0, s[84:85]
	s_mov_b32 m0, s10
	s_nop 0
	global_load_lds_dwordx4 v[156:157], off
	v_lshl_add_u64 v[156:157], v[234:235], 0, s[84:85]
	s_add_i32 m0, s10, 0x2000
	s_nop 0
	global_load_lds_dwordx4 v[156:157], off
	v_lshl_add_u64 v[156:157], v[236:237], 0, s[84:85]
	s_mov_b32 m0, s79
	s_nop 0
	global_load_lds_dwordx4 v[156:157], off
	v_lshl_add_u64 v[156:157], v[238:239], 0, s[84:85]
	s_mov_b32 m0, s90
	s_nop 0
	global_load_lds_dwordx4 v[156:157], off
	s_waitcnt vmcnt(8)
	s_waitcnt lgkmcnt(0)
	s_barrier
	s_waitcnt lgkmcnt(0)
	v_mfma_f32_16x16x32_bf16 v[60:63], v[148:151], v[198:201], v[60:63]
	v_mfma_f32_16x16x32_bf16 v[56:59], v[174:177], v[198:201], v[56:59]
	v_mfma_f32_16x16x32_bf16 v[44:47], v[148:151], v[206:209], v[44:47]
	v_mfma_f32_16x16x32_bf16 v[40:43], v[174:177], v[206:209], v[40:43]
	v_mfma_f32_16x16x32_bf16 v[28:31], v[148:151], v[214:217], v[28:31]
	v_mfma_f32_16x16x32_bf16 v[24:27], v[174:177], v[214:217], v[24:27]
	v_mfma_f32_16x16x32_bf16 v[12:15], v[148:151], v[222:225], v[12:15]
	v_mfma_f32_16x16x32_bf16 v[8:11], v[174:177], v[222:225], v[8:11]
	v_mfma_f32_16x16x32_bf16 v[60:63], v[152:155], v[202:205], v[60:63]
	v_mfma_f32_16x16x32_bf16 v[56:59], v[178:181], v[202:205], v[56:59]
	v_mfma_f32_16x16x32_bf16 v[44:47], v[152:155], v[210:213], v[44:47]
	v_mfma_f32_16x16x32_bf16 v[40:43], v[178:181], v[210:213], v[40:43]
	v_mfma_f32_16x16x32_bf16 v[28:31], v[152:155], v[218:221], v[28:31]
	v_mfma_f32_16x16x32_bf16 v[24:27], v[178:181], v[218:221], v[24:27]
	v_mfma_f32_16x16x32_bf16 v[12:15], v[152:155], v[226:229], v[12:15]
	v_mfma_f32_16x16x32_bf16 v[8:11], v[178:181], v[226:229], v[8:11]
	v_mfma_f32_16x16x32_bf16 v[52:55], v[182:185], v[198:201], v[52:55]
	v_mfma_f32_16x16x32_bf16 v[48:51], v[190:193], v[198:201], v[48:51]
	v_mfma_f32_16x16x32_bf16 v[36:39], v[182:185], v[206:209], v[36:39]
	v_mfma_f32_16x16x32_bf16 v[32:35], v[190:193], v[206:209], v[32:35]
	v_mfma_f32_16x16x32_bf16 v[20:23], v[182:185], v[214:217], v[20:23]
	v_mfma_f32_16x16x32_bf16 v[16:19], v[190:193], v[214:217], v[16:19]
	v_mfma_f32_16x16x32_bf16 v[0:3], v[182:185], v[222:225], v[0:3]
	v_mfma_f32_16x16x32_bf16 v[4:7], v[190:193], v[222:225], v[4:7]
	v_mfma_f32_16x16x32_bf16 v[52:55], v[186:189], v[202:205], v[52:55]
	v_mfma_f32_16x16x32_bf16 v[48:51], v[194:197], v[202:205], v[48:51]
	v_mfma_f32_16x16x32_bf16 v[36:39], v[186:189], v[210:213], v[36:39]
	v_mfma_f32_16x16x32_bf16 v[32:35], v[194:197], v[210:213], v[32:35]
	v_mfma_f32_16x16x32_bf16 v[20:23], v[186:189], v[218:221], v[20:23]
	v_mfma_f32_16x16x32_bf16 v[16:19], v[194:197], v[218:221], v[16:19]
	v_mfma_f32_16x16x32_bf16 v[0:3], v[186:189], v[226:229], v[0:3]
	v_mfma_f32_16x16x32_bf16 v[4:7], v[194:197], v[226:229], v[4:7]
	s_barrier
	s_add_u32 s24, s24, 0x100
	s_addc_u32 s25, s25, 0
	s_add_u32 s8, s8, 0x100
	s_addc_u32 s9, s9, 0
	s_cmp_ge_u32 s39, s26
	s_mov_b32 s10, s39
	s_branch .LBB0_241

.LBB0_355:
	s_add_u32 s24, s20, 0xfffc0080
	s_addc_u32 s25, s21, -1
	s_add_i32 s50, 0, 0x10000
	s_cmp_eq_u32 s49, 12
	s_cselect_b32 s27, s9, s25
	s_cselect_b32 s26, s19, s24
	v_add_u32_e32 v144, s50, v146
	s_cselect_b32 s25, s11, s48
	s_cselect_b32 s24, s46, s47
	s_add_i32 s77, 0, 0x14000
	ds_read_b128 v[152:155], v144
	ds_read_b128 v[170:173], v144 offset:1024
	ds_read_b128 v[174:177], v144 offset:2048
	ds_read_b128 v[178:181], v144 offset:3072
	v_add_u32_e32 v144, s77, v146
	ds_read_b128 v[182:185], v144
	ds_read_b128 v[186:189], v144 offset:1024
	ds_read_b128 v[190:193], v144 offset:2048
	ds_read_b128 v[194:197], v144 offset:3072
	v_lshl_add_u64 v[144:145], s[20:21], 0, v[140:141]
	s_add_i32 m0, s38, 0xc000
	ds_read_b128 v[198:201], v150
	ds_read_b128 v[202:205], v150 offset:1024
	ds_read_b128 v[206:209], v150 offset:2048
	ds_read_b128 v[210:213], v150 offset:3072
	ds_read_b128 v[214:217], v150 offset:4096
	ds_read_b128 v[218:221], v150 offset:5120
	ds_read_b128 v[222:225], v150 offset:6144
	ds_read_b128 v[226:229], v150 offset:7168
	global_load_lds_dwordx4 v[144:145], off
	v_lshl_add_u64 v[144:145], s[20:21], 0, v[142:143]
	s_add_i32 m0, s38, 0xe000
	s_nop 0
	global_load_lds_dwordx4 v[144:145], off
	s_waitcnt vmcnt(8)
	s_waitcnt lgkmcnt(0)
	s_barrier
	s_waitcnt lgkmcnt(0)
	v_mfma_f32_16x16x32_bf16 v[124:127], v[152:155], v[198:201], v[124:127]
	v_mfma_f32_16x16x32_bf16 v[116:119], v[174:177], v[198:201], v[116:119]
	v_mfma_f32_16x16x32_bf16 v[108:111], v[152:155], v[206:209], v[108:111]
	v_mfma_f32_16x16x32_bf16 v[100:103], v[174:177], v[206:209], v[100:103]
	v_mfma_f32_16x16x32_bf16 v[92:95], v[152:155], v[214:217], v[92:95]
	v_mfma_f32_16x16x32_bf16 v[84:87], v[174:177], v[214:217], v[84:87]
	v_mfma_f32_16x16x32_bf16 v[76:79], v[152:155], v[222:225], v[76:79]
	v_mfma_f32_16x16x32_bf16 v[68:71], v[174:177], v[222:225], v[68:71]
	v_mfma_f32_16x16x32_bf16 v[124:127], v[170:173], v[202:205], v[124:127]
	v_mfma_f32_16x16x32_bf16 v[116:119], v[178:181], v[202:205], v[116:119]
	v_mfma_f32_16x16x32_bf16 v[108:111], v[170:173], v[210:213], v[108:111]
	v_mfma_f32_16x16x32_bf16 v[100:103], v[178:181], v[210:213], v[100:103]
	v_mfma_f32_16x16x32_bf16 v[92:95], v[170:173], v[218:221], v[92:95]
	v_mfma_f32_16x16x32_bf16 v[84:87], v[178:181], v[218:221], v[84:87]
	v_mfma_f32_16x16x32_bf16 v[76:79], v[170:173], v[226:229], v[76:79]
	v_mfma_f32_16x16x32_bf16 v[68:71], v[178:181], v[226:229], v[68:71]
	v_mfma_f32_16x16x32_bf16 v[120:123], v[182:185], v[198:201], v[120:123]
	v_mfma_f32_16x16x32_bf16 v[112:115], v[190:193], v[198:201], v[112:115]
	v_mfma_f32_16x16x32_bf16 v[104:107], v[182:185], v[206:209], v[104:107]
	v_mfma_f32_16x16x32_bf16 v[96:99], v[190:193], v[206:209], v[96:99]
	v_mfma_f32_16x16x32_bf16 v[88:91], v[182:185], v[214:217], v[88:91]
	v_mfma_f32_16x16x32_bf16 v[80:83], v[190:193], v[214:217], v[80:83]
	v_mfma_f32_16x16x32_bf16 v[72:75], v[182:185], v[222:225], v[72:75]
	v_mfma_f32_16x16x32_bf16 v[64:67], v[190:193], v[222:225], v[64:67]
	v_mfma_f32_16x16x32_bf16 v[120:123], v[186:189], v[202:205], v[120:123]
	v_mfma_f32_16x16x32_bf16 v[112:115], v[194:197], v[202:205], v[112:115]
	v_mfma_f32_16x16x32_bf16 v[104:107], v[186:189], v[210:213], v[104:107]
	v_mfma_f32_16x16x32_bf16 v[96:99], v[194:197], v[210:213], v[96:99]
	v_mfma_f32_16x16x32_bf16 v[88:91], v[186:189], v[218:221], v[88:91]
	v_mfma_f32_16x16x32_bf16 v[80:83], v[194:197], v[218:221], v[80:83]
	v_mfma_f32_16x16x32_bf16 v[72:75], v[186:189], v[226:229], v[72:75]
	v_mfma_f32_16x16x32_bf16 v[64:67], v[194:197], v[226:229], v[64:67]
	s_barrier
	s_add_i32 s50, s50, s37
	v_lshl_add_u64 v[144:145], s[24:25], 0, v[128:129]
	s_mov_b32 m0, s50
	ds_read_b128 v[198:201], v150 offset:16384
	ds_read_b128 v[202:205], v150 offset:17408
	ds_read_b128 v[206:209], v150 offset:18432
	ds_read_b128 v[210:213], v150 offset:19456
	ds_read_b128 v[214:217], v150 offset:20480
	ds_read_b128 v[218:221], v150 offset:21504
	ds_read_b128 v[222:225], v150 offset:22528
	ds_read_b128 v[226:229], v150 offset:23552
	global_load_lds_dwordx4 v[144:145], off
	s_add_i32 m0, s50, 0x2000
	s_add_u32 s50, s24, 0x40000
	v_lshl_add_u64 v[156:157], s[24:25], 0, v[134:135]
	s_addc_u32 s51, s25, 0
	s_add_i32 s77, s77, s37
	global_load_lds_dwordx4 v[156:157], off
	v_lshl_add_u64 v[230:231], s[50:51], 0, v[128:129]
	s_mov_b32 m0, s77
	v_lshl_add_u64 v[232:233], s[26:27], 0, v[136:137]
	global_load_lds_dwordx4 v[230:231], off
	v_lshl_add_u64 v[230:231], s[50:51], 0, v[134:135]
	s_add_i32 m0, s77, 0x2000
	s_nop 0
	global_load_lds_dwordx4 v[230:231], off
	v_lshl_add_u64 v[230:231], s[26:27], 0, v[138:139]
	s_mov_b32 m0, s38
	s_nop 0
	global_load_lds_dwordx4 v[230:231], off
	s_mov_b32 m0, s39
	s_nop 0
	global_load_lds_dwordx4 v[232:233], off
	s_waitcnt vmcnt(8)
	s_waitcnt lgkmcnt(0)
	s_barrier
	s_waitcnt lgkmcnt(0)
	v_mfma_f32_16x16x32_bf16 v[60:63], v[152:155], v[198:201], v[60:63]
	v_mfma_f32_16x16x32_bf16 v[52:55], v[174:177], v[198:201], v[52:55]
	v_mfma_f32_16x16x32_bf16 v[44:47], v[152:155], v[206:209], v[44:47]
	v_mfma_f32_16x16x32_bf16 v[36:39], v[174:177], v[206:209], v[36:39]
	v_mfma_f32_16x16x32_bf16 v[28:31], v[152:155], v[214:217], v[28:31]
	v_mfma_f32_16x16x32_bf16 v[20:23], v[174:177], v[214:217], v[20:23]
	v_mfma_f32_16x16x32_bf16 v[12:15], v[152:155], v[222:225], v[12:15]
	v_mfma_f32_16x16x32_bf16 v[4:7], v[174:177], v[222:225], v[4:7]
	v_mfma_f32_16x16x32_bf16 v[60:63], v[170:173], v[202:205], v[60:63]
	v_mfma_f32_16x16x32_bf16 v[52:55], v[178:181], v[202:205], v[52:55]
	v_mfma_f32_16x16x32_bf16 v[44:47], v[170:173], v[210:213], v[44:47]
	v_mfma_f32_16x16x32_bf16 v[36:39], v[178:181], v[210:213], v[36:39]
	v_mfma_f32_16x16x32_bf16 v[28:31], v[170:173], v[218:221], v[28:31]
	v_mfma_f32_16x16x32_bf16 v[20:23], v[178:181], v[218:221], v[20:23]
	v_mfma_f32_16x16x32_bf16 v[12:15], v[170:173], v[226:229], v[12:15]
	v_mfma_f32_16x16x32_bf16 v[4:7], v[178:181], v[226:229], v[4:7]
	v_mfma_f32_16x16x32_bf16 v[56:59], v[182:185], v[198:201], v[56:59]
	v_mfma_f32_16x16x32_bf16 v[48:51], v[190:193], v[198:201], v[48:51]
	v_mfma_f32_16x16x32_bf16 v[40:43], v[182:185], v[206:209], v[40:43]
	v_mfma_f32_16x16x32_bf16 v[32:35], v[190:193], v[206:209], v[32:35]
	v_mfma_f32_16x16x32_bf16 v[24:27], v[182:185], v[214:217], v[24:27]
	v_mfma_f32_16x16x32_bf16 v[16:19], v[190:193], v[214:217], v[16:19]
	v_mfma_f32_16x16x32_bf16 v[8:11], v[182:185], v[222:225], v[8:11]
	v_mfma_f32_16x16x32_bf16 v[0:3], v[190:193], v[222:225], v[0:3]
	v_mfma_f32_16x16x32_bf16 v[56:59], v[186:189], v[202:205], v[56:59]
	v_mfma_f32_16x16x32_bf16 v[48:51], v[194:197], v[202:205], v[48:51]
	v_mfma_f32_16x16x32_bf16 v[40:43], v[186:189], v[210:213], v[40:43]
	v_mfma_f32_16x16x32_bf16 v[32:35], v[194:197], v[210:213], v[32:35]
	v_mfma_f32_16x16x32_bf16 v[24:27], v[186:189], v[218:221], v[24:27]
	v_mfma_f32_16x16x32_bf16 v[16:19], v[194:197], v[218:221], v[16:19]
	v_mfma_f32_16x16x32_bf16 v[8:11], v[186:189], v[226:229], v[8:11]
	v_mfma_f32_16x16x32_bf16 v[0:3], v[194:197], v[226:229], v[0:3]
	s_barrier
	s_add_i32 s50, 0, 0x18000
	v_add_u32_e32 v151, s50, v146
	s_add_i32 s51, 0, 0x1c000
	ds_read_b128 v[152:155], v151
	ds_read_b128 v[170:173], v151 offset:1024
	ds_read_b128 v[174:177], v151 offset:2048
	ds_read_b128 v[178:181], v151 offset:3072
	v_add_u32_e32 v151, s51, v146
	ds_read_b128 v[182:185], v151
	ds_read_b128 v[186:189], v151 offset:1024
	ds_read_b128 v[190:193], v151 offset:2048
	ds_read_b128 v[194:197], v151 offset:3072
	s_add_u32 s26, s26, 0x40000
	s_addc_u32 s27, s27, 0
	s_mov_b32 m0, s40
	v_lshl_add_u64 v[234:235], s[26:27], 0, v[138:139]
	ds_read_b128 v[198:201], v150 offset:32768
	ds_read_b128 v[202:205], v150 offset:33792
	ds_read_b128 v[206:209], v150 offset:34816
	ds_read_b128 v[210:213], v150 offset:35840
	ds_read_b128 v[214:217], v150 offset:36864
	ds_read_b128 v[218:221], v150 offset:37888
	ds_read_b128 v[222:225], v150 offset:38912
	ds_read_b128 v[226:229], v150 offset:39936
	global_load_lds_dwordx4 v[234:235], off
	v_lshl_add_u64 v[234:235], s[26:27], 0, v[136:137]
	s_mov_b32 m0, s41
	s_nop 0
	global_load_lds_dwordx4 v[234:235], off
	s_waitcnt vmcnt(8)
	s_waitcnt lgkmcnt(0)
	s_barrier
	s_waitcnt lgkmcnt(0)
	v_mfma_f32_16x16x32_bf16 v[124:127], v[152:155], v[198:201], v[124:127]
	v_mfma_f32_16x16x32_bf16 v[116:119], v[174:177], v[198:201], v[116:119]
	v_mfma_f32_16x16x32_bf16 v[108:111], v[152:155], v[206:209], v[108:111]
	v_mfma_f32_16x16x32_bf16 v[100:103], v[174:177], v[206:209], v[100:103]
	v_mfma_f32_16x16x32_bf16 v[92:95], v[152:155], v[214:217], v[92:95]
	v_mfma_f32_16x16x32_bf16 v[84:87], v[174:177], v[214:217], v[84:87]
	v_mfma_f32_16x16x32_bf16 v[76:79], v[152:155], v[222:225], v[76:79]
	v_mfma_f32_16x16x32_bf16 v[68:71], v[174:177], v[222:225], v[68:71]
	v_mfma_f32_16x16x32_bf16 v[124:127], v[170:173], v[202:205], v[124:127]
	v_mfma_f32_16x16x32_bf16 v[116:119], v[178:181], v[202:205], v[116:119]
	v_mfma_f32_16x16x32_bf16 v[108:111], v[170:173], v[210:213], v[108:111]
	v_mfma_f32_16x16x32_bf16 v[100:103], v[178:181], v[210:213], v[100:103]
	v_mfma_f32_16x16x32_bf16 v[92:95], v[170:173], v[218:221], v[92:95]
	v_mfma_f32_16x16x32_bf16 v[84:87], v[178:181], v[218:221], v[84:87]
	v_mfma_f32_16x16x32_bf16 v[76:79], v[170:173], v[226:229], v[76:79]
	v_mfma_f32_16x16x32_bf16 v[68:71], v[178:181], v[226:229], v[68:71]
	v_mfma_f32_16x16x32_bf16 v[120:123], v[182:185], v[198:201], v[120:123]
	v_mfma_f32_16x16x32_bf16 v[112:115], v[190:193], v[198:201], v[112:115]
	v_mfma_f32_16x16x32_bf16 v[104:107], v[182:185], v[206:209], v[104:107]
	v_mfma_f32_16x16x32_bf16 v[96:99], v[190:193], v[206:209], v[96:99]
	v_mfma_f32_16x16x32_bf16 v[88:91], v[182:185], v[214:217], v[88:91]
	v_mfma_f32_16x16x32_bf16 v[80:83], v[190:193], v[214:217], v[80:83]
	v_mfma_f32_16x16x32_bf16 v[72:75], v[182:185], v[222:225], v[72:75]
	v_mfma_f32_16x16x32_bf16 v[64:67], v[190:193], v[222:225], v[64:67]
	v_mfma_f32_16x16x32_bf16 v[120:123], v[186:189], v[202:205], v[120:123]
	v_mfma_f32_16x16x32_bf16 v[112:115], v[194:197], v[202:205], v[112:115]
	v_mfma_f32_16x16x32_bf16 v[104:107], v[186:189], v[210:213], v[104:107]
	v_mfma_f32_16x16x32_bf16 v[96:99], v[194:197], v[210:213], v[96:99]
	v_mfma_f32_16x16x32_bf16 v[88:91], v[186:189], v[218:221], v[88:91]
	v_mfma_f32_16x16x32_bf16 v[80:83], v[194:197], v[218:221], v[80:83]
	v_mfma_f32_16x16x32_bf16 v[72:75], v[186:189], v[226:229], v[72:75]
	v_mfma_f32_16x16x32_bf16 v[64:67], v[194:197], v[226:229], v[64:67]
	s_barrier
	s_add_i32 s26, s50, s37
	v_lshl_add_u64 v[144:145], v[144:145], 0, s[84:85]
	s_mov_b32 m0, s26
	ds_read_b128 v[198:201], v150 offset:49152
	ds_read_b128 v[202:205], v150 offset:50176
	ds_read_b128 v[206:209], v150 offset:51200
	ds_read_b128 v[210:213], v150 offset:52224
	ds_read_b128 v[214:217], v150 offset:53248
	ds_read_b128 v[218:221], v150 offset:54272
	ds_read_b128 v[222:225], v150 offset:55296
	ds_read_b128 v[226:229], v150 offset:56320
	global_load_lds_dwordx4 v[144:145], off
	s_add_i32 m0, s26, 0x2000
	s_add_u32 s24, s24, 0x40080
	v_lshl_add_u64 v[144:145], v[156:157], 0, s[84:85]
	s_addc_u32 s25, s25, 0
	s_add_i32 s26, s51, s37
	global_load_lds_dwordx4 v[144:145], off
	v_lshl_add_u64 v[144:145], s[24:25], 0, v[128:129]
	s_mov_b32 m0, s26
	s_nop 0
	global_load_lds_dwordx4 v[144:145], off
	v_lshl_add_u64 v[144:145], s[24:25], 0, v[134:135]
	s_add_i32 m0, s26, 0x2000
	s_nop 0
	global_load_lds_dwordx4 v[144:145], off
	v_lshl_add_u64 v[144:145], v[230:231], 0, s[84:85]
	s_mov_b32 m0, s42
	s_nop 0
	global_load_lds_dwordx4 v[144:145], off
	v_lshl_add_u64 v[144:145], v[232:233], 0, s[84:85]
	s_mov_b32 m0, s43
	s_nop 0
	global_load_lds_dwordx4 v[144:145], off
	s_waitcnt vmcnt(8)
	s_waitcnt lgkmcnt(0)
	s_barrier
	s_waitcnt lgkmcnt(0)
	v_mfma_f32_16x16x32_bf16 v[60:63], v[152:155], v[198:201], v[60:63]
	v_mfma_f32_16x16x32_bf16 v[52:55], v[174:177], v[198:201], v[52:55]
	v_mfma_f32_16x16x32_bf16 v[44:47], v[152:155], v[206:209], v[44:47]
	v_mfma_f32_16x16x32_bf16 v[36:39], v[174:177], v[206:209], v[36:39]
	v_mfma_f32_16x16x32_bf16 v[28:31], v[152:155], v[214:217], v[28:31]
	v_mfma_f32_16x16x32_bf16 v[20:23], v[174:177], v[214:217], v[20:23]
	v_mfma_f32_16x16x32_bf16 v[12:15], v[152:155], v[222:225], v[12:15]
	v_mfma_f32_16x16x32_bf16 v[4:7], v[174:177], v[222:225], v[4:7]
	v_mfma_f32_16x16x32_bf16 v[60:63], v[170:173], v[202:205], v[60:63]
	v_mfma_f32_16x16x32_bf16 v[52:55], v[178:181], v[202:205], v[52:55]
	v_mfma_f32_16x16x32_bf16 v[44:47], v[170:173], v[210:213], v[44:47]
	v_mfma_f32_16x16x32_bf16 v[36:39], v[178:181], v[210:213], v[36:39]
	v_mfma_f32_16x16x32_bf16 v[28:31], v[170:173], v[218:221], v[28:31]
	v_mfma_f32_16x16x32_bf16 v[20:23], v[178:181], v[218:221], v[20:23]
	v_mfma_f32_16x16x32_bf16 v[12:15], v[170:173], v[226:229], v[12:15]
	v_mfma_f32_16x16x32_bf16 v[4:7], v[178:181], v[226:229], v[4:7]
	v_mfma_f32_16x16x32_bf16 v[56:59], v[182:185], v[198:201], v[56:59]
	v_mfma_f32_16x16x32_bf16 v[48:51], v[190:193], v[198:201], v[48:51]
	v_mfma_f32_16x16x32_bf16 v[40:43], v[182:185], v[206:209], v[40:43]
	v_mfma_f32_16x16x32_bf16 v[32:35], v[190:193], v[206:209], v[32:35]
	v_mfma_f32_16x16x32_bf16 v[24:27], v[182:185], v[214:217], v[24:27]
	v_mfma_f32_16x16x32_bf16 v[16:19], v[190:193], v[214:217], v[16:19]
	v_mfma_f32_16x16x32_bf16 v[8:11], v[182:185], v[222:225], v[8:11]
	v_mfma_f32_16x16x32_bf16 v[0:3], v[190:193], v[222:225], v[0:3]
	v_mfma_f32_16x16x32_bf16 v[56:59], v[186:189], v[202:205], v[56:59]
	v_mfma_f32_16x16x32_bf16 v[48:51], v[194:197], v[202:205], v[48:51]
	v_mfma_f32_16x16x32_bf16 v[40:43], v[186:189], v[210:213], v[40:43]
	v_mfma_f32_16x16x32_bf16 v[32:35], v[194:197], v[210:213], v[32:35]
	v_mfma_f32_16x16x32_bf16 v[24:27], v[186:189], v[218:221], v[24:27]
	v_mfma_f32_16x16x32_bf16 v[16:19], v[194:197], v[218:221], v[16:19]
	v_mfma_f32_16x16x32_bf16 v[8:11], v[186:189], v[226:229], v[8:11]
	v_mfma_f32_16x16x32_bf16 v[0:3], v[194:197], v[226:229], v[0:3]
	s_barrier
	s_add_i32 s49, s49, 2
	s_add_u32 s20, s20, 0x100
	s_addc_u32 s21, s21, 0
	s_add_u32 s47, s47, 0x100
	s_addc_u32 s48, s48, 0
	s_cmp_gt_u32 s49, 13
	s_cbranch_scc0 .LBB0_355
	s_branch .Lit0_swi_skip
.Lit0_swi:
	s_add_u32 s24, s20, 0xfffc0080
	s_addc_u32 s25, s21, -1
	s_add_i32 s50, 0, 0x10000
	s_cmp_eq_u32 s49, 12
	s_cselect_b32 s27, s9, s25
	s_cselect_b32 s26, s19, s24
	v_add_u32_e32 v144, s50, v146
	s_cselect_b32 s25, s11, s48
	s_cselect_b32 s24, s46, s47
	s_add_i32 s77, 0, 0x14000
	ds_read_b128 v[152:155], v144
	ds_read_b128 v[170:173], v144 offset:1024
	ds_read_b128 v[174:177], v144 offset:2048
	ds_read_b128 v[178:181], v144 offset:3072
	v_add_u32_e32 v144, s77, v146
	ds_read_b128 v[182:185], v144
	ds_read_b128 v[186:189], v144 offset:1024
	ds_read_b128 v[190:193], v144 offset:2048
	ds_read_b128 v[194:197], v144 offset:3072
	v_lshl_add_u64 v[144:145], s[20:21], 0, v[140:141]
	s_add_i32 m0, s38, 0xc000
	ds_read_b128 v[198:201], v150
	ds_read_b128 v[202:205], v150 offset:1024
	ds_read_b128 v[206:209], v150 offset:2048
	ds_read_b128 v[210:213], v150 offset:3072
	ds_read_b128 v[214:217], v150 offset:4096
	ds_read_b128 v[218:221], v150 offset:5120
	ds_read_b128 v[222:225], v150 offset:6144
	ds_read_b128 v[226:229], v150 offset:7168
	global_load_lds_dwordx4 v[144:145], off
	v_lshl_add_u64 v[144:145], s[20:21], 0, v[142:143]
	s_add_i32 m0, s38, 0xe000
	s_nop 0
	global_load_lds_dwordx4 v[144:145], off
	s_waitcnt vmcnt(8)
	s_waitcnt lgkmcnt(0)
	s_barrier
	s_waitcnt lgkmcnt(0)
	v_mfma_f32_16x16x32_bf16 v[124:127], v[152:155], v[198:201], 0
	v_mfma_f32_16x16x32_bf16 v[116:119], v[174:177], v[198:201], 0
	v_mfma_f32_16x16x32_bf16 v[108:111], v[152:155], v[206:209], 0
	v_mfma_f32_16x16x32_bf16 v[100:103], v[174:177], v[206:209], 0
	v_mfma_f32_16x16x32_bf16 v[92:95], v[152:155], v[214:217], 0
	v_mfma_f32_16x16x32_bf16 v[84:87], v[174:177], v[214:217], 0
	v_mfma_f32_16x16x32_bf16 v[76:79], v[152:155], v[222:225], 0
	v_mfma_f32_16x16x32_bf16 v[68:71], v[174:177], v[222:225], 0
	v_mfma_f32_16x16x32_bf16 v[124:127], v[170:173], v[202:205], v[124:127]
	v_mfma_f32_16x16x32_bf16 v[116:119], v[178:181], v[202:205], v[116:119]
	v_mfma_f32_16x16x32_bf16 v[108:111], v[170:173], v[210:213], v[108:111]
	v_mfma_f32_16x16x32_bf16 v[100:103], v[178:181], v[210:213], v[100:103]
	v_mfma_f32_16x16x32_bf16 v[92:95], v[170:173], v[218:221], v[92:95]
	v_mfma_f32_16x16x32_bf16 v[84:87], v[178:181], v[218:221], v[84:87]
	v_mfma_f32_16x16x32_bf16 v[76:79], v[170:173], v[226:229], v[76:79]
	v_mfma_f32_16x16x32_bf16 v[68:71], v[178:181], v[226:229], v[68:71]
	v_mfma_f32_16x16x32_bf16 v[120:123], v[182:185], v[198:201], 0
	v_mfma_f32_16x16x32_bf16 v[112:115], v[190:193], v[198:201], 0
	v_mfma_f32_16x16x32_bf16 v[104:107], v[182:185], v[206:209], 0
	v_mfma_f32_16x16x32_bf16 v[96:99], v[190:193], v[206:209], 0
	v_mfma_f32_16x16x32_bf16 v[88:91], v[182:185], v[214:217], 0
	v_mfma_f32_16x16x32_bf16 v[80:83], v[190:193], v[214:217], 0
	v_mfma_f32_16x16x32_bf16 v[72:75], v[182:185], v[222:225], 0
	v_mfma_f32_16x16x32_bf16 v[64:67], v[190:193], v[222:225], 0
	v_mfma_f32_16x16x32_bf16 v[120:123], v[186:189], v[202:205], v[120:123]
	v_mfma_f32_16x16x32_bf16 v[112:115], v[194:197], v[202:205], v[112:115]
	v_mfma_f32_16x16x32_bf16 v[104:107], v[186:189], v[210:213], v[104:107]
	v_mfma_f32_16x16x32_bf16 v[96:99], v[194:197], v[210:213], v[96:99]
	v_mfma_f32_16x16x32_bf16 v[88:91], v[186:189], v[218:221], v[88:91]
	v_mfma_f32_16x16x32_bf16 v[80:83], v[194:197], v[218:221], v[80:83]
	v_mfma_f32_16x16x32_bf16 v[72:75], v[186:189], v[226:229], v[72:75]
	v_mfma_f32_16x16x32_bf16 v[64:67], v[194:197], v[226:229], v[64:67]
	s_barrier
	s_add_i32 s50, s50, s37
	v_lshl_add_u64 v[144:145], s[24:25], 0, v[128:129]
	s_mov_b32 m0, s50
	ds_read_b128 v[198:201], v150 offset:16384
	ds_read_b128 v[202:205], v150 offset:17408
	ds_read_b128 v[206:209], v150 offset:18432
	ds_read_b128 v[210:213], v150 offset:19456
	ds_read_b128 v[214:217], v150 offset:20480
	ds_read_b128 v[218:221], v150 offset:21504
	ds_read_b128 v[222:225], v150 offset:22528
	ds_read_b128 v[226:229], v150 offset:23552
	global_load_lds_dwordx4 v[144:145], off
	s_add_i32 m0, s50, 0x2000
	s_add_u32 s50, s24, 0x40000
	v_lshl_add_u64 v[156:157], s[24:25], 0, v[134:135]
	s_addc_u32 s51, s25, 0
	s_add_i32 s77, s77, s37
	global_load_lds_dwordx4 v[156:157], off
	v_lshl_add_u64 v[230:231], s[50:51], 0, v[128:129]
	s_mov_b32 m0, s77
	v_lshl_add_u64 v[232:233], s[26:27], 0, v[136:137]
	global_load_lds_dwordx4 v[230:231], off
	v_lshl_add_u64 v[230:231], s[50:51], 0, v[134:135]
	s_add_i32 m0, s77, 0x2000
	s_nop 0
	global_load_lds_dwordx4 v[230:231], off
	v_lshl_add_u64 v[230:231], s[26:27], 0, v[138:139]
	s_mov_b32 m0, s38
	s_nop 0
	global_load_lds_dwordx4 v[230:231], off
	s_mov_b32 m0, s39
	s_nop 0
	global_load_lds_dwordx4 v[232:233], off
	s_waitcnt vmcnt(8)
	s_waitcnt lgkmcnt(0)
	s_barrier
	s_waitcnt lgkmcnt(0)
	v_mfma_f32_16x16x32_bf16 v[60:63], v[152:155], v[198:201], 0
	v_mfma_f32_16x16x32_bf16 v[52:55], v[174:177], v[198:201], 0
	v_mfma_f32_16x16x32_bf16 v[44:47], v[152:155], v[206:209], 0
	v_mfma_f32_16x16x32_bf16 v[36:39], v[174:177], v[206:209], 0
	v_mfma_f32_16x16x32_bf16 v[28:31], v[152:155], v[214:217], 0
	v_mfma_f32_16x16x32_bf16 v[20:23], v[174:177], v[214:217], 0
	v_mfma_f32_16x16x32_bf16 v[12:15], v[152:155], v[222:225], 0
	v_mfma_f32_16x16x32_bf16 v[4:7], v[174:177], v[222:225], 0
	v_mfma_f32_16x16x32_bf16 v[60:63], v[170:173], v[202:205], v[60:63]
	v_mfma_f32_16x16x32_bf16 v[52:55], v[178:181], v[202:205], v[52:55]
	v_mfma_f32_16x16x32_bf16 v[44:47], v[170:173], v[210:213], v[44:47]
	v_mfma_f32_16x16x32_bf16 v[36:39], v[178:181], v[210:213], v[36:39]
	v_mfma_f32_16x16x32_bf16 v[28:31], v[170:173], v[218:221], v[28:31]
	v_mfma_f32_16x16x32_bf16 v[20:23], v[178:181], v[218:221], v[20:23]
	v_mfma_f32_16x16x32_bf16 v[12:15], v[170:173], v[226:229], v[12:15]
	v_mfma_f32_16x16x32_bf16 v[4:7], v[178:181], v[226:229], v[4:7]
	v_mfma_f32_16x16x32_bf16 v[56:59], v[182:185], v[198:201], 0
	v_mfma_f32_16x16x32_bf16 v[48:51], v[190:193], v[198:201], 0
	v_mfma_f32_16x16x32_bf16 v[40:43], v[182:185], v[206:209], 0
	v_mfma_f32_16x16x32_bf16 v[32:35], v[190:193], v[206:209], 0
	v_mfma_f32_16x16x32_bf16 v[24:27], v[182:185], v[214:217], 0
	v_mfma_f32_16x16x32_bf16 v[16:19], v[190:193], v[214:217], 0
	v_mfma_f32_16x16x32_bf16 v[8:11], v[182:185], v[222:225], 0
	v_mfma_f32_16x16x32_bf16 v[0:3], v[190:193], v[222:225], 0
	v_mfma_f32_16x16x32_bf16 v[56:59], v[186:189], v[202:205], v[56:59]
	v_mfma_f32_16x16x32_bf16 v[48:51], v[194:197], v[202:205], v[48:51]
	v_mfma_f32_16x16x32_bf16 v[40:43], v[186:189], v[210:213], v[40:43]
	v_mfma_f32_16x16x32_bf16 v[32:35], v[194:197], v[210:213], v[32:35]
	v_mfma_f32_16x16x32_bf16 v[24:27], v[186:189], v[218:221], v[24:27]
	v_mfma_f32_16x16x32_bf16 v[16:19], v[194:197], v[218:221], v[16:19]
	v_mfma_f32_16x16x32_bf16 v[8:11], v[186:189], v[226:229], v[8:11]
	v_mfma_f32_16x16x32_bf16 v[0:3], v[194:197], v[226:229], v[0:3]
	s_barrier
	s_add_i32 s50, 0, 0x18000
	v_add_u32_e32 v151, s50, v146
	s_add_i32 s51, 0, 0x1c000
	ds_read_b128 v[152:155], v151
	ds_read_b128 v[170:173], v151 offset:1024
	ds_read_b128 v[174:177], v151 offset:2048
	ds_read_b128 v[178:181], v151 offset:3072
	v_add_u32_e32 v151, s51, v146
	ds_read_b128 v[182:185], v151
	ds_read_b128 v[186:189], v151 offset:1024
	ds_read_b128 v[190:193], v151 offset:2048
	ds_read_b128 v[194:197], v151 offset:3072
	s_add_u32 s26, s26, 0x40000
	s_addc_u32 s27, s27, 0
	s_mov_b32 m0, s40
	v_lshl_add_u64 v[234:235], s[26:27], 0, v[138:139]
	ds_read_b128 v[198:201], v150 offset:32768
	ds_read_b128 v[202:205], v150 offset:33792
	ds_read_b128 v[206:209], v150 offset:34816
	ds_read_b128 v[210:213], v150 offset:35840
	ds_read_b128 v[214:217], v150 offset:36864
	ds_read_b128 v[218:221], v150 offset:37888
	ds_read_b128 v[222:225], v150 offset:38912
	ds_read_b128 v[226:229], v150 offset:39936
	global_load_lds_dwordx4 v[234:235], off
	v_lshl_add_u64 v[234:235], s[26:27], 0, v[136:137]
	s_mov_b32 m0, s41
	s_nop 0
	global_load_lds_dwordx4 v[234:235], off
	s_waitcnt vmcnt(8)
	s_waitcnt lgkmcnt(0)
	s_barrier
	s_waitcnt lgkmcnt(0)
	v_mfma_f32_16x16x32_bf16 v[124:127], v[152:155], v[198:201], v[124:127]
	v_mfma_f32_16x16x32_bf16 v[116:119], v[174:177], v[198:201], v[116:119]
	v_mfma_f32_16x16x32_bf16 v[108:111], v[152:155], v[206:209], v[108:111]
	v_mfma_f32_16x16x32_bf16 v[100:103], v[174:177], v[206:209], v[100:103]
	v_mfma_f32_16x16x32_bf16 v[92:95], v[152:155], v[214:217], v[92:95]
	v_mfma_f32_16x16x32_bf16 v[84:87], v[174:177], v[214:217], v[84:87]
	v_mfma_f32_16x16x32_bf16 v[76:79], v[152:155], v[222:225], v[76:79]
	v_mfma_f32_16x16x32_bf16 v[68:71], v[174:177], v[222:225], v[68:71]
	v_mfma_f32_16x16x32_bf16 v[124:127], v[170:173], v[202:205], v[124:127]
	v_mfma_f32_16x16x32_bf16 v[116:119], v[178:181], v[202:205], v[116:119]
	v_mfma_f32_16x16x32_bf16 v[108:111], v[170:173], v[210:213], v[108:111]
	v_mfma_f32_16x16x32_bf16 v[100:103], v[178:181], v[210:213], v[100:103]
	v_mfma_f32_16x16x32_bf16 v[92:95], v[170:173], v[218:221], v[92:95]
	v_mfma_f32_16x16x32_bf16 v[84:87], v[178:181], v[218:221], v[84:87]
	v_mfma_f32_16x16x32_bf16 v[76:79], v[170:173], v[226:229], v[76:79]
	v_mfma_f32_16x16x32_bf16 v[68:71], v[178:181], v[226:229], v[68:71]
	v_mfma_f32_16x16x32_bf16 v[120:123], v[182:185], v[198:201], v[120:123]
	v_mfma_f32_16x16x32_bf16 v[112:115], v[190:193], v[198:201], v[112:115]
	v_mfma_f32_16x16x32_bf16 v[104:107], v[182:185], v[206:209], v[104:107]
	v_mfma_f32_16x16x32_bf16 v[96:99], v[190:193], v[206:209], v[96:99]
	v_mfma_f32_16x16x32_bf16 v[88:91], v[182:185], v[214:217], v[88:91]
	v_mfma_f32_16x16x32_bf16 v[80:83], v[190:193], v[214:217], v[80:83]
	v_mfma_f32_16x16x32_bf16 v[72:75], v[182:185], v[222:225], v[72:75]
	v_mfma_f32_16x16x32_bf16 v[64:67], v[190:193], v[222:225], v[64:67]
	v_mfma_f32_16x16x32_bf16 v[120:123], v[186:189], v[202:205], v[120:123]
	v_mfma_f32_16x16x32_bf16 v[112:115], v[194:197], v[202:205], v[112:115]
	v_mfma_f32_16x16x32_bf16 v[104:107], v[186:189], v[210:213], v[104:107]
	v_mfma_f32_16x16x32_bf16 v[96:99], v[194:197], v[210:213], v[96:99]
	v_mfma_f32_16x16x32_bf16 v[88:91], v[186:189], v[218:221], v[88:91]
	v_mfma_f32_16x16x32_bf16 v[80:83], v[194:197], v[218:221], v[80:83]
	v_mfma_f32_16x16x32_bf16 v[72:75], v[186:189], v[226:229], v[72:75]
	v_mfma_f32_16x16x32_bf16 v[64:67], v[194:197], v[226:229], v[64:67]
	s_barrier
	s_add_i32 s26, s50, s37
	v_lshl_add_u64 v[144:145], v[144:145], 0, s[84:85]
	s_mov_b32 m0, s26
	ds_read_b128 v[198:201], v150 offset:49152
	ds_read_b128 v[202:205], v150 offset:50176
	ds_read_b128 v[206:209], v150 offset:51200
	ds_read_b128 v[210:213], v150 offset:52224
	ds_read_b128 v[214:217], v150 offset:53248
	ds_read_b128 v[218:221], v150 offset:54272
	ds_read_b128 v[222:225], v150 offset:55296
	ds_read_b128 v[226:229], v150 offset:56320
	global_load_lds_dwordx4 v[144:145], off
	s_add_i32 m0, s26, 0x2000
	s_add_u32 s24, s24, 0x40080
	v_lshl_add_u64 v[144:145], v[156:157], 0, s[84:85]
	s_addc_u32 s25, s25, 0
	s_add_i32 s26, s51, s37
	global_load_lds_dwordx4 v[144:145], off
	v_lshl_add_u64 v[144:145], s[24:25], 0, v[128:129]
	s_mov_b32 m0, s26
	s_nop 0
	global_load_lds_dwordx4 v[144:145], off
	v_lshl_add_u64 v[144:145], s[24:25], 0, v[134:135]
	s_add_i32 m0, s26, 0x2000
	s_nop 0
	global_load_lds_dwordx4 v[144:145], off
	v_lshl_add_u64 v[144:145], v[230:231], 0, s[84:85]
	s_mov_b32 m0, s42
	s_nop 0
	global_load_lds_dwordx4 v[144:145], off
	v_lshl_add_u64 v[144:145], v[232:233], 0, s[84:85]
	s_mov_b32 m0, s43
	s_nop 0
	global_load_lds_dwordx4 v[144:145], off
	s_waitcnt vmcnt(8)
	s_waitcnt lgkmcnt(0)
	s_barrier
	s_waitcnt lgkmcnt(0)
	v_mfma_f32_16x16x32_bf16 v[60:63], v[152:155], v[198:201], v[60:63]
	v_mfma_f32_16x16x32_bf16 v[52:55], v[174:177], v[198:201], v[52:55]
	v_mfma_f32_16x16x32_bf16 v[44:47], v[152:155], v[206:209], v[44:47]
	v_mfma_f32_16x16x32_bf16 v[36:39], v[174:177], v[206:209], v[36:39]
	v_mfma_f32_16x16x32_bf16 v[28:31], v[152:155], v[214:217], v[28:31]
	v_mfma_f32_16x16x32_bf16 v[20:23], v[174:177], v[214:217], v[20:23]
	v_mfma_f32_16x16x32_bf16 v[12:15], v[152:155], v[222:225], v[12:15]
	v_mfma_f32_16x16x32_bf16 v[4:7], v[174:177], v[222:225], v[4:7]
	v_mfma_f32_16x16x32_bf16 v[60:63], v[170:173], v[202:205], v[60:63]
	v_mfma_f32_16x16x32_bf16 v[52:55], v[178:181], v[202:205], v[52:55]
	v_mfma_f32_16x16x32_bf16 v[44:47], v[170:173], v[210:213], v[44:47]
	v_mfma_f32_16x16x32_bf16 v[36:39], v[178:181], v[210:213], v[36:39]
	v_mfma_f32_16x16x32_bf16 v[28:31], v[170:173], v[218:221], v[28:31]
	v_mfma_f32_16x16x32_bf16 v[20:23], v[178:181], v[218:221], v[20:23]
	v_mfma_f32_16x16x32_bf16 v[12:15], v[170:173], v[226:229], v[12:15]
	v_mfma_f32_16x16x32_bf16 v[4:7], v[178:181], v[226:229], v[4:7]
	v_mfma_f32_16x16x32_bf16 v[56:59], v[182:185], v[198:201], v[56:59]
	v_mfma_f32_16x16x32_bf16 v[48:51], v[190:193], v[198:201], v[48:51]
	v_mfma_f32_16x16x32_bf16 v[40:43], v[182:185], v[206:209], v[40:43]
	v_mfma_f32_16x16x32_bf16 v[32:35], v[190:193], v[206:209], v[32:35]
	v_mfma_f32_16x16x32_bf16 v[24:27], v[182:185], v[214:217], v[24:27]
	v_mfma_f32_16x16x32_bf16 v[16:19], v[190:193], v[214:217], v[16:19]
	v_mfma_f32_16x16x32_bf16 v[8:11], v[182:185], v[222:225], v[8:11]
	v_mfma_f32_16x16x32_bf16 v[0:3], v[190:193], v[222:225], v[0:3]
	v_mfma_f32_16x16x32_bf16 v[56:59], v[186:189], v[202:205], v[56:59]
	v_mfma_f32_16x16x32_bf16 v[48:51], v[194:197], v[202:205], v[48:51]
	v_mfma_f32_16x16x32_bf16 v[40:43], v[186:189], v[210:213], v[40:43]
	v_mfma_f32_16x16x32_bf16 v[32:35], v[194:197], v[210:213], v[32:35]
	v_mfma_f32_16x16x32_bf16 v[24:27], v[186:189], v[218:221], v[24:27]
	v_mfma_f32_16x16x32_bf16 v[16:19], v[194:197], v[218:221], v[16:19]
	v_mfma_f32_16x16x32_bf16 v[8:11], v[186:189], v[226:229], v[8:11]
	v_mfma_f32_16x16x32_bf16 v[0:3], v[194:197], v[226:229], v[0:3]
	s_barrier
	s_add_i32 s49, s49, 2
	s_add_u32 s20, s20, 0x100
	s_addc_u32 s21, s21, 0
	s_add_u32 s47, s47, 0x100
	s_addc_u32 s48, s48, 0
	s_cmp_gt_u32 s49, 13
	s_branch .LBB0_355
